# K-loops: one static s_setprio 1 for waves 4-7, no per-phase flips
# baseline (speedup 1.0000x reference)
.LBB0_100:
	s_cmp_ge_u32 s9, 0x1000
	s_cbranch_scc0 .Lsp_0
	s_setprio 1
.Lsp_0:
	ds_read_b128 v[146:149], v143
	ds_read_b128 v[150:153], v143 offset:1024
	ds_read_b128 v[154:157], v143 offset:2048
	ds_read_b128 v[158:161], v143 offset:3072
	s_add_u32 s20, s18, 0xfffc0080
	s_addc_u32 s21, s19, -1
	s_cmp_eq_u32 s62, 12
	s_cselect_b32 s23, s11, s21
	s_cselect_b32 s22, s50, s20
	s_cselect_b32 s21, s13, s61
	s_cselect_b32 s20, s51, s60
	v_lshl_add_u64 v[194:195], s[18:19], 0, v[132:133]
	s_add_i32 m0, s9, 0xc000
	ds_read_b128 v[162:165], v144
	ds_read_b128 v[166:169], v144 offset:1024
	ds_read_b128 v[170:173], v144 offset:2048
	ds_read_b128 v[174:177], v144 offset:3072
	ds_read_b128 v[178:181], v144 offset:4096
	ds_read_b128 v[182:185], v144 offset:5120
	ds_read_b128 v[186:189], v144 offset:6144
	ds_read_b128 v[190:193], v144 offset:7168
	global_load_lds_dwordx4 v[194:195], off
	v_lshl_add_u64 v[194:195], s[18:19], 0, v[134:135]
	s_add_i32 m0, s9, 0xe000
	s_nop 0
	global_load_lds_dwordx4 v[194:195], off
	s_waitcnt lgkmcnt(8)
	s_barrier
	s_waitcnt lgkmcnt(0)
	s_waitcnt lgkmcnt(0)
	v_mfma_f32_16x16x32_bf16 v[124:127], v[146:149], v[162:165], v[124:127]
	v_mfma_f32_16x16x32_bf16 v[120:123], v[154:157], v[162:165], v[120:123]
	v_mfma_f32_16x16x32_bf16 v[116:119], v[146:149], v[170:173], v[116:119]
	v_mfma_f32_16x16x32_bf16 v[108:111], v[154:157], v[170:173], v[108:111]
	v_mfma_f32_16x16x32_bf16 v[100:103], v[146:149], v[178:181], v[100:103]
	v_mfma_f32_16x16x32_bf16 v[92:95], v[154:157], v[178:181], v[92:95]
	v_mfma_f32_16x16x32_bf16 v[84:87], v[146:149], v[186:189], v[84:87]
	v_mfma_f32_16x16x32_bf16 v[76:79], v[154:157], v[186:189], v[76:79]
	v_mfma_f32_16x16x32_bf16 v[124:127], v[150:153], v[166:169], v[124:127]
	v_mfma_f32_16x16x32_bf16 v[120:123], v[158:161], v[166:169], v[120:123]
	v_mfma_f32_16x16x32_bf16 v[116:119], v[150:153], v[174:177], v[116:119]
	v_mfma_f32_16x16x32_bf16 v[108:111], v[158:161], v[174:177], v[108:111]
	v_mfma_f32_16x16x32_bf16 v[100:103], v[150:153], v[182:185], v[100:103]
	v_mfma_f32_16x16x32_bf16 v[92:95], v[158:161], v[182:185], v[92:95]
	v_mfma_f32_16x16x32_bf16 v[84:87], v[150:153], v[190:193], v[84:87]
	v_mfma_f32_16x16x32_bf16 v[76:79], v[158:161], v[190:193], v[76:79]
	s_barrier
	s_add_i32 s63, s47, s35
	v_lshl_add_u64 v[210:211], s[20:21], 0, v[128:129]
	s_mov_b32 m0, s63
	ds_read_b128 v[194:197], v145
	ds_read_b128 v[198:201], v145 offset:1024
	ds_read_b128 v[202:205], v145 offset:2048
	ds_read_b128 v[206:209], v145 offset:3072
	global_load_lds_dwordx4 v[210:211], off
	v_lshl_add_u64 v[212:213], s[20:21], 0, v[130:131]
	s_add_i32 m0, s63, 0x2000
	s_nop 0
	global_load_lds_dwordx4 v[212:213], off
	s_barrier
	s_waitcnt lgkmcnt(0)
	s_waitcnt lgkmcnt(0)
	v_mfma_f32_16x16x32_bf16 v[112:115], v[194:197], v[162:165], v[112:115]
	v_mfma_f32_16x16x32_bf16 v[104:107], v[202:205], v[162:165], v[104:107]
	v_mfma_f32_16x16x32_bf16 v[96:99], v[194:197], v[170:173], v[96:99]
	v_mfma_f32_16x16x32_bf16 v[88:91], v[202:205], v[170:173], v[88:91]
	v_mfma_f32_16x16x32_bf16 v[80:83], v[194:197], v[178:181], v[80:83]
	v_mfma_f32_16x16x32_bf16 v[72:75], v[202:205], v[178:181], v[72:75]
	v_mfma_f32_16x16x32_bf16 v[68:71], v[194:197], v[186:189], v[68:71]
	v_mfma_f32_16x16x32_bf16 v[64:67], v[202:205], v[186:189], v[64:67]
	v_mfma_f32_16x16x32_bf16 v[112:115], v[198:201], v[166:169], v[112:115]
	v_mfma_f32_16x16x32_bf16 v[104:107], v[206:209], v[166:169], v[104:107]
	v_mfma_f32_16x16x32_bf16 v[96:99], v[198:201], v[174:177], v[96:99]
	v_mfma_f32_16x16x32_bf16 v[88:91], v[206:209], v[174:177], v[88:91]
	v_mfma_f32_16x16x32_bf16 v[80:83], v[198:201], v[182:185], v[80:83]
	v_mfma_f32_16x16x32_bf16 v[72:75], v[206:209], v[182:185], v[72:75]
	v_mfma_f32_16x16x32_bf16 v[68:71], v[198:201], v[190:193], v[68:71]
	v_mfma_f32_16x16x32_bf16 v[64:67], v[206:209], v[190:193], v[64:67]
	s_mov_b32 m0, s9
	v_lshl_add_u64 v[214:215], s[22:23], 0, v[128:129]
	s_barrier
	ds_read_b128 v[162:165], v144 offset:16384
	ds_read_b128 v[166:169], v144 offset:17408
	ds_read_b128 v[170:173], v144 offset:18432
	ds_read_b128 v[174:177], v144 offset:19456
	ds_read_b128 v[178:181], v144 offset:20480
	ds_read_b128 v[182:185], v144 offset:21504
	ds_read_b128 v[186:189], v144 offset:22528
	ds_read_b128 v[190:193], v144 offset:23552
	global_load_lds_dwordx4 v[214:215], off
	v_lshl_add_u64 v[216:217], s[22:23], 0, v[130:131]
	s_mov_b32 m0, s36
	s_nop 0
	global_load_lds_dwordx4 v[216:217], off
	s_barrier
	s_waitcnt lgkmcnt(0)
	s_waitcnt lgkmcnt(0)
	v_mfma_f32_16x16x32_bf16 v[60:63], v[146:149], v[162:165], v[60:63]
	v_mfma_f32_16x16x32_bf16 v[56:59], v[154:157], v[162:165], v[56:59]
	v_mfma_f32_16x16x32_bf16 v[52:55], v[146:149], v[170:173], v[52:55]
	v_mfma_f32_16x16x32_bf16 v[48:51], v[154:157], v[170:173], v[48:51]
	v_mfma_f32_16x16x32_bf16 v[36:39], v[146:149], v[178:181], v[36:39]
	v_mfma_f32_16x16x32_bf16 v[32:35], v[154:157], v[178:181], v[32:35]
	v_mfma_f32_16x16x32_bf16 v[20:23], v[146:149], v[186:189], v[20:23]
	v_mfma_f32_16x16x32_bf16 v[16:19], v[154:157], v[186:189], v[16:19]
	v_mfma_f32_16x16x32_bf16 v[60:63], v[150:153], v[166:169], v[60:63]
	v_mfma_f32_16x16x32_bf16 v[56:59], v[158:161], v[166:169], v[56:59]
	v_mfma_f32_16x16x32_bf16 v[52:55], v[150:153], v[174:177], v[52:55]
	v_mfma_f32_16x16x32_bf16 v[48:51], v[158:161], v[174:177], v[48:51]
	v_mfma_f32_16x16x32_bf16 v[36:39], v[150:153], v[182:185], v[36:39]
	v_mfma_f32_16x16x32_bf16 v[32:35], v[158:161], v[182:185], v[32:35]
	v_mfma_f32_16x16x32_bf16 v[20:23], v[150:153], v[190:193], v[20:23]
	v_mfma_f32_16x16x32_bf16 v[16:19], v[158:161], v[190:193], v[16:19]
	s_barrier
	s_add_u32 s68, s20, 0x40000
	s_addc_u32 s69, s21, 0
	s_add_i32 s63, s48, s35
	v_lshl_add_u64 v[146:147], s[68:69], 0, v[128:129]
	s_mov_b32 m0, s63
	s_nop 0
	global_load_lds_dwordx4 v[146:147], off
	v_lshl_add_u64 v[146:147], s[68:69], 0, v[130:131]
	s_add_i32 m0, s63, 0x2000
	s_nop 0
	global_load_lds_dwordx4 v[146:147], off
	s_waitcnt vmcnt(6)
	s_barrier
	v_mfma_f32_16x16x32_bf16 v[44:47], v[194:197], v[162:165], v[44:47]
	v_mfma_f32_16x16x32_bf16 v[40:43], v[202:205], v[162:165], v[40:43]
	v_mfma_f32_16x16x32_bf16 v[28:31], v[194:197], v[170:173], v[28:31]
	v_mfma_f32_16x16x32_bf16 v[24:27], v[202:205], v[170:173], v[24:27]
	v_mfma_f32_16x16x32_bf16 v[12:15], v[194:197], v[178:181], v[12:15]
	v_mfma_f32_16x16x32_bf16 v[8:11], v[202:205], v[178:181], v[8:11]
	v_mfma_f32_16x16x32_bf16 v[4:7], v[194:197], v[186:189], v[4:7]
	v_mfma_f32_16x16x32_bf16 v[0:3], v[202:205], v[186:189], v[0:3]
	v_mfma_f32_16x16x32_bf16 v[44:47], v[198:201], v[166:169], v[44:47]
	v_mfma_f32_16x16x32_bf16 v[40:43], v[206:209], v[166:169], v[40:43]
	v_mfma_f32_16x16x32_bf16 v[28:31], v[198:201], v[174:177], v[28:31]
	v_mfma_f32_16x16x32_bf16 v[24:27], v[206:209], v[174:177], v[24:27]
	v_mfma_f32_16x16x32_bf16 v[12:15], v[198:201], v[182:185], v[12:15]
	v_mfma_f32_16x16x32_bf16 v[8:11], v[206:209], v[182:185], v[8:11]
	v_mfma_f32_16x16x32_bf16 v[4:7], v[198:201], v[190:193], v[4:7]
	v_mfma_f32_16x16x32_bf16 v[0:3], v[206:209], v[190:193], v[0:3]
	s_add_i32 s63, 0, 0x18000
	v_add_u32_e32 v158, s63, v141
	s_barrier
	ds_read_b128 v[146:149], v158
	ds_read_b128 v[150:153], v158 offset:1024
	ds_read_b128 v[154:157], v158 offset:2048
	ds_read_b128 v[158:161], v158 offset:3072
	s_add_u32 s22, s22, 0x40000
	s_addc_u32 s23, s23, 0
	s_mov_b32 m0, s37
	v_lshl_add_u64 v[194:195], s[22:23], 0, v[128:129]
	ds_read_b128 v[162:165], v144 offset:32768
	ds_read_b128 v[166:169], v144 offset:33792
	ds_read_b128 v[170:173], v144 offset:34816
	ds_read_b128 v[174:177], v144 offset:35840
	ds_read_b128 v[178:181], v144 offset:36864
	ds_read_b128 v[182:185], v144 offset:37888
	ds_read_b128 v[186:189], v144 offset:38912
	ds_read_b128 v[190:193], v144 offset:39936
	global_load_lds_dwordx4 v[194:195], off
	v_lshl_add_u64 v[194:195], s[22:23], 0, v[130:131]
	s_mov_b32 m0, s38
	s_nop 0
	global_load_lds_dwordx4 v[194:195], off
	s_waitcnt lgkmcnt(8)
	s_barrier
	s_waitcnt lgkmcnt(0)
	s_waitcnt lgkmcnt(0)
	v_mfma_f32_16x16x32_bf16 v[124:127], v[146:149], v[162:165], v[124:127]
	v_mfma_f32_16x16x32_bf16 v[120:123], v[154:157], v[162:165], v[120:123]
	v_mfma_f32_16x16x32_bf16 v[116:119], v[146:149], v[170:173], v[116:119]
	v_mfma_f32_16x16x32_bf16 v[108:111], v[154:157], v[170:173], v[108:111]
	v_mfma_f32_16x16x32_bf16 v[100:103], v[146:149], v[178:181], v[100:103]
	v_mfma_f32_16x16x32_bf16 v[92:95], v[154:157], v[178:181], v[92:95]
	v_mfma_f32_16x16x32_bf16 v[84:87], v[146:149], v[186:189], v[84:87]
	v_mfma_f32_16x16x32_bf16 v[76:79], v[154:157], v[186:189], v[76:79]
	v_mfma_f32_16x16x32_bf16 v[124:127], v[150:153], v[166:169], v[124:127]
	v_mfma_f32_16x16x32_bf16 v[120:123], v[158:161], v[166:169], v[120:123]
	v_mfma_f32_16x16x32_bf16 v[116:119], v[150:153], v[174:177], v[116:119]
	v_mfma_f32_16x16x32_bf16 v[108:111], v[158:161], v[174:177], v[108:111]
	v_mfma_f32_16x16x32_bf16 v[100:103], v[150:153], v[182:185], v[100:103]
	v_mfma_f32_16x16x32_bf16 v[92:95], v[158:161], v[182:185], v[92:95]
	v_mfma_f32_16x16x32_bf16 v[84:87], v[150:153], v[190:193], v[84:87]
	v_mfma_f32_16x16x32_bf16 v[76:79], v[158:161], v[190:193], v[76:79]
	s_barrier
	s_add_i32 s22, 0, 0x1c000
	s_add_i32 s23, s63, s35
	v_add_u32_e32 v206, s22, v141
	v_lshl_add_u64 v[210:211], v[210:211], 0, s[6:7]
	s_mov_b32 m0, s23
	ds_read_b128 v[194:197], v206
	ds_read_b128 v[198:201], v206 offset:1024
	ds_read_b128 v[202:205], v206 offset:2048
	ds_read_b128 v[206:209], v206 offset:3072
	global_load_lds_dwordx4 v[210:211], off
	v_lshl_add_u64 v[210:211], v[212:213], 0, s[6:7]
	s_add_i32 m0, s23, 0x2000
	s_nop 0
	global_load_lds_dwordx4 v[210:211], off
	s_barrier
	s_waitcnt lgkmcnt(0)
	s_waitcnt lgkmcnt(0)
	v_mfma_f32_16x16x32_bf16 v[112:115], v[194:197], v[162:165], v[112:115]
	v_mfma_f32_16x16x32_bf16 v[104:107], v[202:205], v[162:165], v[104:107]
	v_mfma_f32_16x16x32_bf16 v[96:99], v[194:197], v[170:173], v[96:99]
	v_mfma_f32_16x16x32_bf16 v[88:91], v[202:205], v[170:173], v[88:91]
	v_mfma_f32_16x16x32_bf16 v[80:83], v[194:197], v[178:181], v[80:83]
	v_mfma_f32_16x16x32_bf16 v[72:75], v[202:205], v[178:181], v[72:75]
	v_mfma_f32_16x16x32_bf16 v[68:71], v[194:197], v[186:189], v[68:71]
	v_mfma_f32_16x16x32_bf16 v[64:67], v[202:205], v[186:189], v[64:67]
	v_mfma_f32_16x16x32_bf16 v[112:115], v[198:201], v[166:169], v[112:115]
	v_mfma_f32_16x16x32_bf16 v[104:107], v[206:209], v[166:169], v[104:107]
	v_mfma_f32_16x16x32_bf16 v[96:99], v[198:201], v[174:177], v[96:99]
	v_mfma_f32_16x16x32_bf16 v[88:91], v[206:209], v[174:177], v[88:91]
	v_mfma_f32_16x16x32_bf16 v[80:83], v[198:201], v[182:185], v[80:83]
	v_mfma_f32_16x16x32_bf16 v[72:75], v[206:209], v[182:185], v[72:75]
	v_mfma_f32_16x16x32_bf16 v[68:71], v[198:201], v[190:193], v[68:71]
	v_mfma_f32_16x16x32_bf16 v[64:67], v[206:209], v[190:193], v[64:67]
	s_mov_b32 m0, s41
	v_lshl_add_u64 v[210:211], v[214:215], 0, s[6:7]
	s_barrier
	ds_read_b128 v[162:165], v144 offset:49152
	ds_read_b128 v[166:169], v144 offset:50176
	ds_read_b128 v[170:173], v144 offset:51200
	ds_read_b128 v[174:177], v144 offset:52224
	ds_read_b128 v[178:181], v144 offset:53248
	ds_read_b128 v[182:185], v144 offset:54272
	ds_read_b128 v[186:189], v144 offset:55296
	ds_read_b128 v[190:193], v144 offset:56320
	global_load_lds_dwordx4 v[210:211], off
	v_lshl_add_u64 v[210:211], v[216:217], 0, s[6:7]
	s_mov_b32 m0, s43
	s_nop 0
	global_load_lds_dwordx4 v[210:211], off
	s_barrier
	s_waitcnt lgkmcnt(0)
	s_waitcnt lgkmcnt(0)
	v_mfma_f32_16x16x32_bf16 v[60:63], v[146:149], v[162:165], v[60:63]
	v_mfma_f32_16x16x32_bf16 v[56:59], v[154:157], v[162:165], v[56:59]
	v_mfma_f32_16x16x32_bf16 v[52:55], v[146:149], v[170:173], v[52:55]
	v_mfma_f32_16x16x32_bf16 v[48:51], v[154:157], v[170:173], v[48:51]
	v_mfma_f32_16x16x32_bf16 v[36:39], v[146:149], v[178:181], v[36:39]
	v_mfma_f32_16x16x32_bf16 v[32:35], v[154:157], v[178:181], v[32:35]
	v_mfma_f32_16x16x32_bf16 v[20:23], v[146:149], v[186:189], v[20:23]
	v_mfma_f32_16x16x32_bf16 v[16:19], v[154:157], v[186:189], v[16:19]
	v_mfma_f32_16x16x32_bf16 v[60:63], v[150:153], v[166:169], v[60:63]
	v_mfma_f32_16x16x32_bf16 v[56:59], v[158:161], v[166:169], v[56:59]
	v_mfma_f32_16x16x32_bf16 v[52:55], v[150:153], v[174:177], v[52:55]
	v_mfma_f32_16x16x32_bf16 v[48:51], v[158:161], v[174:177], v[48:51]
	v_mfma_f32_16x16x32_bf16 v[36:39], v[150:153], v[182:185], v[36:39]
	v_mfma_f32_16x16x32_bf16 v[32:35], v[158:161], v[182:185], v[32:35]
	v_mfma_f32_16x16x32_bf16 v[20:23], v[150:153], v[190:193], v[20:23]
	v_mfma_f32_16x16x32_bf16 v[16:19], v[158:161], v[190:193], v[16:19]
	s_barrier
	s_add_u32 s20, s20, 0x40080
	s_addc_u32 s21, s21, 0
	s_add_i32 s22, s22, s35
	v_lshl_add_u64 v[146:147], s[20:21], 0, v[128:129]
	s_mov_b32 m0, s22
	s_nop 0
	global_load_lds_dwordx4 v[146:147], off
	v_lshl_add_u64 v[146:147], s[20:21], 0, v[130:131]
	s_add_i32 m0, s22, 0x2000
	s_nop 0
	global_load_lds_dwordx4 v[146:147], off
	s_waitcnt vmcnt(6)
	s_barrier
	v_mfma_f32_16x16x32_bf16 v[44:47], v[194:197], v[162:165], v[44:47]
	v_mfma_f32_16x16x32_bf16 v[40:43], v[202:205], v[162:165], v[40:43]
	v_mfma_f32_16x16x32_bf16 v[28:31], v[194:197], v[170:173], v[28:31]
	v_mfma_f32_16x16x32_bf16 v[24:27], v[202:205], v[170:173], v[24:27]
	v_mfma_f32_16x16x32_bf16 v[12:15], v[194:197], v[178:181], v[12:15]
	v_mfma_f32_16x16x32_bf16 v[8:11], v[202:205], v[178:181], v[8:11]
	v_mfma_f32_16x16x32_bf16 v[4:7], v[194:197], v[186:189], v[4:7]
	v_mfma_f32_16x16x32_bf16 v[0:3], v[202:205], v[186:189], v[0:3]
	v_mfma_f32_16x16x32_bf16 v[44:47], v[198:201], v[166:169], v[44:47]
	v_mfma_f32_16x16x32_bf16 v[40:43], v[206:209], v[166:169], v[40:43]
	v_mfma_f32_16x16x32_bf16 v[28:31], v[198:201], v[174:177], v[28:31]
	v_mfma_f32_16x16x32_bf16 v[24:27], v[206:209], v[174:177], v[24:27]
	v_mfma_f32_16x16x32_bf16 v[12:15], v[198:201], v[182:185], v[12:15]
	v_mfma_f32_16x16x32_bf16 v[8:11], v[206:209], v[182:185], v[8:11]
	v_mfma_f32_16x16x32_bf16 v[4:7], v[198:201], v[190:193], v[4:7]
	v_mfma_f32_16x16x32_bf16 v[0:3], v[206:209], v[190:193], v[0:3]
	s_add_i32 s62, s62, 2
	s_add_u32 s18, s18, 0x100
	s_addc_u32 s19, s19, 0
	s_add_u32 s60, s60, 0x100
	s_addc_u32 s61, s61, 0
	s_cmp_gt_u32 s62, 13
	s_barrier
	s_cbranch_scc0 .LBB0_100
	s_setprio 0
	v_lshl_add_u32 v148, s8, 8, v140
	v_lshl_or_b32 v146, s49, 8, v142
	v_ashrrev_i32_e32 v149, 31, v148
	v_cvt_pk_bf16_f32 v112, v112, v113
	v_cvt_pk_bf16_f32 v113, v114, v115
	v_cvt_pk_bf16_f32 v114, v104, v105
	v_or_b32_e32 v104, 16, v148
	v_ashrrev_i32_e32 v147, 31, v146
	v_lshlrev_b64 v[150:151], 11, v[148:149]
	v_ashrrev_i32_e32 v105, 31, v104
	v_cvt_pk_bf16_f32 v96, v96, v97
	v_cvt_pk_bf16_f32 v97, v98, v99
	v_cvt_pk_bf16_f32 v98, v88, v89
	v_or_b32_e32 v88, 32, v148
	v_lshl_add_u64 v[150:151], s[2:3], 0, v[150:151]
	v_lshlrev_b64 v[146:147], 1, v[146:147]
	v_lshlrev_b64 v[104:105], 11, v[104:105]
	v_ashrrev_i32_e32 v89, 31, v88
	v_cvt_pk_bf16_f32 v80, v80, v81
	v_cvt_pk_bf16_f32 v81, v82, v83
	v_cvt_pk_bf16_f32 v82, v72, v73
	v_or_b32_e32 v72, 48, v148
	v_cvt_pk_bf16_f32 v68, v68, v69
	v_cvt_pk_bf16_f32 v69, v70, v71
	v_cvt_pk_bf16_f32 v70, v64, v65
	v_add_u32_e32 v64, 0x80, v148
	v_lshl_add_u64 v[150:151], v[150:151], 0, v[146:147]
	v_cvt_pk_bf16_f32 v124, v124, v125
	v_cvt_pk_bf16_f32 v125, v126, v127
	v_cvt_pk_bf16_f32 v126, v120, v121
	v_cvt_pk_bf16_f32 v127, v122, v123
	v_lshl_add_u64 v[104:105], s[2:3], 0, v[104:105]
	v_lshlrev_b64 v[88:89], 11, v[88:89]
	v_ashrrev_i32_e32 v73, 31, v72
	v_ashrrev_i32_e32 v65, 31, v64
	v_cvt_pk_bf16_f32 v44, v44, v45
	v_cvt_pk_bf16_f32 v45, v46, v47
	v_cvt_pk_bf16_f32 v46, v40, v41
	v_add_u32_e32 v40, 0x90, v148
	v_cvt_pk_bf16_f32 v115, v106, v107
	global_store_dwordx4 v[150:151], v[124:127], off
	global_store_dwordx4 v[150:151], v[112:115], off offset:64
	v_cvt_pk_bf16_f32 v106, v108, v109
	v_cvt_pk_bf16_f32 v107, v110, v111
	v_lshl_add_u64 v[112:113], v[104:105], 0, v[146:147]
	v_cvt_pk_bf16_f32 v104, v116, v117
	v_cvt_pk_bf16_f32 v105, v118, v119
	v_lshl_add_u64 v[88:89], s[2:3], 0, v[88:89]
	v_lshlrev_b64 v[72:73], 11, v[72:73]
	v_lshlrev_b64 v[64:65], 11, v[64:65]
	v_ashrrev_i32_e32 v41, 31, v40
	v_cvt_pk_bf16_f32 v28, v28, v29
	v_cvt_pk_bf16_f32 v29, v30, v31
	v_cvt_pk_bf16_f32 v30, v24, v25
	v_add_u32_e32 v24, 0xa0, v148
	v_cvt_pk_bf16_f32 v99, v90, v91
	global_store_dwordx4 v[112:113], v[104:107], off
	global_store_dwordx4 v[112:113], v[96:99], off offset:64
	v_cvt_pk_bf16_f32 v90, v92, v93
	v_cvt_pk_bf16_f32 v91, v94, v95
	v_lshl_add_u64 v[96:97], v[88:89], 0, v[146:147]
	v_cvt_pk_bf16_f32 v88, v100, v101
	v_cvt_pk_bf16_f32 v89, v102, v103
	v_lshl_add_u64 v[72:73], s[2:3], 0, v[72:73]
	v_lshl_add_u64 v[64:65], s[2:3], 0, v[64:65]
	v_lshlrev_b64 v[40:41], 11, v[40:41]
	v_ashrrev_i32_e32 v25, 31, v24
	v_cvt_pk_bf16_f32 v12, v12, v13
	v_cvt_pk_bf16_f32 v13, v14, v15
	v_cvt_pk_bf16_f32 v14, v8, v9
	v_add_u32_e32 v8, 0xb0, v148
	v_cvt_pk_bf16_f32 v83, v74, v75
	global_store_dwordx4 v[96:97], v[88:91], off
	global_store_dwordx4 v[96:97], v[80:83], off offset:64
	v_cvt_pk_bf16_f32 v74, v76, v77
	v_cvt_pk_bf16_f32 v75, v78, v79
	v_lshl_add_u64 v[80:81], v[72:73], 0, v[146:147]
	v_cvt_pk_bf16_f32 v72, v84, v85
	v_cvt_pk_bf16_f32 v73, v86, v87
	v_lshl_add_u64 v[64:65], v[64:65], 0, v[146:147]
	v_cvt_pk_bf16_f32 v60, v60, v61
	v_cvt_pk_bf16_f32 v61, v62, v63
	v_cvt_pk_bf16_f32 v62, v56, v57
	v_cvt_pk_bf16_f32 v63, v58, v59
	v_lshl_add_u64 v[40:41], s[2:3], 0, v[40:41]
	v_lshlrev_b64 v[24:25], 11, v[24:25]
	v_ashrrev_i32_e32 v9, 31, v8
	v_cvt_pk_bf16_f32 v71, v66, v67
	global_store_dwordx4 v[80:81], v[72:75], off
	global_store_dwordx4 v[80:81], v[68:71], off offset:64
	v_cvt_pk_bf16_f32 v47, v42, v43
	global_store_dwordx4 v[64:65], v[60:63], off
	global_store_dwordx4 v[64:65], v[44:47], off offset:64
	v_cvt_pk_bf16_f32 v42, v48, v49
	v_cvt_pk_bf16_f32 v43, v50, v51
	v_lshl_add_u64 v[44:45], v[40:41], 0, v[146:147]
	v_cvt_pk_bf16_f32 v40, v52, v53
	v_cvt_pk_bf16_f32 v41, v54, v55
	v_lshl_add_u64 v[24:25], s[2:3], 0, v[24:25]
	v_lshlrev_b64 v[8:9], 11, v[8:9]
	v_cvt_pk_bf16_f32 v31, v26, v27
	global_store_dwordx4 v[44:45], v[40:43], off
	global_store_dwordx4 v[44:45], v[28:31], off offset:64
	v_cvt_pk_bf16_f32 v26, v32, v33
	v_cvt_pk_bf16_f32 v27, v34, v35
	v_lshl_add_u64 v[28:29], v[24:25], 0, v[146:147]
	v_cvt_pk_bf16_f32 v24, v36, v37
	v_cvt_pk_bf16_f32 v25, v38, v39
	v_lshl_add_u64 v[8:9], s[2:3], 0, v[8:9]
	v_cvt_pk_bf16_f32 v15, v10, v11
	global_store_dwordx4 v[28:29], v[24:27], off
	global_store_dwordx4 v[28:29], v[12:15], off offset:64
	v_cvt_pk_bf16_f32 v10, v16, v17
	v_cvt_pk_bf16_f32 v11, v18, v19
	v_lshl_add_u64 v[12:13], v[8:9], 0, v[146:147]
	v_cvt_pk_bf16_f32 v8, v20, v21
	v_cvt_pk_bf16_f32 v9, v22, v23
	s_and_b64 vcc, exec, s[4:5]
	s_mov_b32 s49, s12
	s_mov_b32 s8, s10
	s_mov_b64 s[20:21], s[16:17]
	s_mov_b64 s[18:19], s[14:15]
	v_cvt_pk_bf16_f32 v4, v4, v5
	v_cvt_pk_bf16_f32 v5, v6, v7
	v_cvt_pk_bf16_f32 v6, v0, v1
	v_cvt_pk_bf16_f32 v7, v2, v3
	global_store_dwordx4 v[12:13], v[8:11], off
	global_store_dwordx4 v[12:13], v[4:7], off offset:64
	s_cbranch_vccz .LBB0_93
	s_waitcnt vmcnt(0)
	s_cmpk_gt_u32 s27, 0xff
	s_cbranch_scc1 .LBB0_104
	s_barrier

.LBB0_174:
	v_lshrrev_b32_e32 v18, 1, v15
	s_add_u32 s46, s9, 0x19c00000
	v_and_b32_e32 v18, 24, v18
	s_addc_u32 s47, s10, 0
	v_and_b32_e32 v16, 15, v15
	s_lshl_b32 s17, s1, 6
	v_lshlrev_b32_e32 v19, 1, v18
	v_lshlrev_b32_e32 v15, 2, v15
	s_and_b32 s6, s0, 3
	v_or_b32_e32 v17, s17, v16
	v_lshl_or_b32 v16, v16, 6, v19
	s_lshl_b32 s0, s1, 13
	v_and_b32_e32 v15, 32, v15
	s_add_i32 m0, s73, 0x18000
	v_lshl_add_u64 v[8:9], v[8:9], 0, s[24:25]
	v_bitop3_b32 v19, v16, s0, v15 bitop3:0xde
	s_lshl_b32 s0, s6, 12
	s_waitcnt vmcnt(4)
	s_barrier
	global_load_lds_dwordx4 v[8:9], off
	v_lshl_add_u64 v[6:7], v[6:7], 0, s[24:25]
	s_add_i32 m0, s73, 0x1a000
	s_add_i32 s18, s73, 0x8000
	s_add_i32 s19, s73, 0xa000
	v_bitop3_b32 v155, v16, s0, v15 bitop3:0xde
	global_load_lds_dwordx4 v[6:7], off
	v_lshl_add_u64 v[4:5], v[4:5], 0, s[24:25]
	s_mov_b32 m0, s18
	s_add_u32 s0, s62, 0x40080
	global_load_lds_dwordx4 v[4:5], off
	v_lshl_add_u64 v[2:3], v[2:3], 0, s[24:25]
	s_mov_b32 m0, s19
	s_addc_u32 s1, s63, 0
	global_load_lds_dwordx4 v[2:3], off
	s_add_i32 m0, s73, 0x1c000
	v_lshl_add_u64 v[2:3], s[0:1], 0, v[146:147]
	global_load_lds_dwordx4 v[2:3], off
	v_lshl_add_u64 v[2:3], s[0:1], 0, v[148:149]
	s_add_i32 m0, s73, 0x1e000
	v_add_u32_e32 v245, 0x80, v17
	global_load_lds_dwordx4 v[2:3], off
	v_lshlrev_b32_e32 v2, 8, v17
	v_and_b32_e32 v244, 0xcf00, v2
	v_lshlrev_b32_e32 v2, 8, v245
	v_add_u32_e32 v247, 0x90, v17
	v_and_b32_e32 v246, 0xcf00, v2
	v_lshlrev_b32_e32 v2, 8, v247
	v_add_u32_e32 v249, 0xa0, v17
	v_and_b32_e32 v248, 0xdf00, v2
	v_lshlrev_b32_e32 v2, 8, v249
	v_add_u32_e32 v251, 0xb0, v17
	v_and_b32_e32 v250, 0xef00, v2
	v_lshlrev_b32_e32 v2, 8, v251
	v_and_b32_e32 v252, 0xff00, v2
	v_lshlrev_b32_e32 v2, 14, v0
	v_and_b32_e32 v2, 0xffff8000, v2
	v_lshl_add_u32 v2, v10, 11, v2
	v_and_b32_e32 v0, 1, v0
	v_lshl_or_b32 v0, v0, 6, v2
	v_lshl_add_u32 v150, v11, 1, v0
	v_lshlrev_b32_e32 v0, 14, v12
	v_and_b32_e32 v0, 0xffff8000, v0
	s_waitcnt vmcnt(6)
	v_lshl_add_u32 v0, v13, 11, v0
	v_and_b32_e32 v2, 1, v12
	s_add_i32 s0, 0, 0x20000
	v_lshl_or_b32 v0, v2, 6, v0
	v_lshl_add_u32 v179, v18, 2, s0
	s_ashr_i32 s20, s48, 31
	v_lshl_or_b32 v253, s6, 6, v18
	v_mov_b32_e32 v151, v1
	v_lshl_add_u32 v152, v14, 1, v0
	v_mov_b32_e32 v153, v1
	s_mov_b32 s21, 0
	v_add_u32_e32 v231, 0, v19
	s_barrier
	s_branch .LBB0_176
	s_nop 0
	s_nop 0
	s_nop 0
	s_nop 0
	s_nop 0
	s_nop 0
	s_nop 0
	s_nop 0
	s_nop 0
	s_nop 0
	s_nop 0

.LBB0_179:
	s_cmp_ge_u32 s73, 0x1000
	s_cbranch_scc0 .Lsp_1
	s_setprio 1
.Lsp_1:
	s_add_u32 s6, s2, 0xfffc0080
	s_addc_u32 s7, s3, -1
	s_add_i32 s33, 0, 0x10000
	v_add_u32_e32 v0, s33, v155
	ds_read_b128 v[130:133], v0
	ds_read_b128 v[134:137], v0 offset:1024
	ds_read_b128 v[138:141], v0 offset:2048
	ds_read_b128 v[142:145], v0 offset:3072
	s_cmp_eq_u32 vcc_hi, 12
	s_cselect_b32 s91, s1, s7
	s_cselect_b32 s90, s22, s6
	s_cselect_b32 s63, s23, vcc_lo
	s_cselect_b32 s62, s39, s69
	v_lshl_add_u64 v[176:177], s[2:3], 0, v[150:151]
	s_add_i32 m0, s73, 0xc000
	ds_read_b128 v[156:159], v231
	ds_read_b128 v[160:163], v231 offset:1024
	ds_read_b128 v[164:167], v231 offset:2048
	ds_read_b128 v[168:171], v231 offset:3072
	ds_read_b128 v[172:175], v231 offset:4096
	ds_read_b128 v[184:187], v231 offset:5120
	ds_read_b128 v[188:191], v231 offset:6144
	ds_read_b128 v[192:195], v231 offset:7168
	global_load_lds_dwordx4 v[176:177], off
	v_lshl_add_u64 v[176:177], s[2:3], 0, v[152:153]
	s_add_i32 m0, s73, 0xe000
	s_nop 0
	global_load_lds_dwordx4 v[176:177], off
	s_waitcnt lgkmcnt(8)
	s_barrier
	s_waitcnt lgkmcnt(0)
	s_waitcnt lgkmcnt(0)
	v_mfma_f32_16x16x32_bf16 v[126:129], v[130:133], v[156:159], v[126:129]
	v_mfma_f32_16x16x32_bf16 v[122:125], v[138:141], v[156:159], v[122:125]
	v_mfma_f32_16x16x32_bf16 v[110:113], v[130:133], v[164:167], v[110:113]
	v_mfma_f32_16x16x32_bf16 v[106:109], v[138:141], v[164:167], v[106:109]
	v_mfma_f32_16x16x32_bf16 v[94:97], v[130:133], v[172:175], v[94:97]
	v_mfma_f32_16x16x32_bf16 v[90:93], v[138:141], v[172:175], v[90:93]
	v_mfma_f32_16x16x32_bf16 v[78:81], v[130:133], v[188:191], v[78:81]
	v_mfma_f32_16x16x32_bf16 v[74:77], v[138:141], v[188:191], v[74:77]
	v_mfma_f32_16x16x32_bf16 v[126:129], v[134:137], v[160:163], v[126:129]
	v_mfma_f32_16x16x32_bf16 v[122:125], v[142:145], v[160:163], v[122:125]
	v_mfma_f32_16x16x32_bf16 v[110:113], v[134:137], v[168:171], v[110:113]
	v_mfma_f32_16x16x32_bf16 v[106:109], v[142:145], v[168:171], v[106:109]
	v_mfma_f32_16x16x32_bf16 v[94:97], v[134:137], v[184:187], v[94:97]
	v_mfma_f32_16x16x32_bf16 v[90:93], v[142:145], v[184:187], v[90:93]
	v_mfma_f32_16x16x32_bf16 v[78:81], v[134:137], v[192:195], v[78:81]
	v_mfma_f32_16x16x32_bf16 v[74:77], v[142:145], v[192:195], v[74:77]
	s_barrier
	s_add_i32 s94, 0, 0x14000
	s_add_i32 s6, s33, s11
	v_add_u32_e32 v0, s94, v155
	v_lshl_add_u64 v[176:177], s[62:63], 0, v[146:147]
	s_mov_b32 m0, s6
	ds_read_b128 v[196:199], v0
	ds_read_b128 v[200:203], v0 offset:1024
	ds_read_b128 v[204:207], v0 offset:2048
	ds_read_b128 v[208:211], v0 offset:3072
	global_load_lds_dwordx4 v[176:177], off
	v_lshl_add_u64 v[180:181], s[62:63], 0, v[148:149]
	s_add_i32 m0, s6, 0x2000
	s_nop 0
	global_load_lds_dwordx4 v[180:181], off
	s_barrier
	s_waitcnt lgkmcnt(0)
	s_waitcnt lgkmcnt(0)
	v_mfma_f32_16x16x32_bf16 v[118:121], v[196:199], v[156:159], v[118:121]
	v_mfma_f32_16x16x32_bf16 v[114:117], v[204:207], v[156:159], v[114:117]
	v_mfma_f32_16x16x32_bf16 v[102:105], v[196:199], v[164:167], v[102:105]
	v_mfma_f32_16x16x32_bf16 v[98:101], v[204:207], v[164:167], v[98:101]
	v_mfma_f32_16x16x32_bf16 v[86:89], v[196:199], v[172:175], v[86:89]
	v_mfma_f32_16x16x32_bf16 v[82:85], v[204:207], v[172:175], v[82:85]
	v_mfma_f32_16x16x32_bf16 v[70:73], v[196:199], v[188:191], v[70:73]
	v_mfma_f32_16x16x32_bf16 v[66:69], v[204:207], v[188:191], v[66:69]
	v_mfma_f32_16x16x32_bf16 v[118:121], v[200:203], v[160:163], v[118:121]
	v_mfma_f32_16x16x32_bf16 v[114:117], v[208:211], v[160:163], v[114:117]
	v_mfma_f32_16x16x32_bf16 v[102:105], v[200:203], v[168:171], v[102:105]
	v_mfma_f32_16x16x32_bf16 v[98:101], v[208:211], v[168:171], v[98:101]
	v_mfma_f32_16x16x32_bf16 v[86:89], v[200:203], v[184:187], v[86:89]
	v_mfma_f32_16x16x32_bf16 v[82:85], v[208:211], v[184:187], v[82:85]
	v_mfma_f32_16x16x32_bf16 v[70:73], v[200:203], v[192:195], v[70:73]
	v_mfma_f32_16x16x32_bf16 v[66:69], v[208:211], v[192:195], v[66:69]
	s_mov_b32 m0, s73
	v_lshl_add_u64 v[212:213], s[90:91], 0, v[146:147]
	s_barrier
	ds_read_b128 v[156:159], v231 offset:16384
	ds_read_b128 v[160:163], v231 offset:17408
	ds_read_b128 v[164:167], v231 offset:18432
	ds_read_b128 v[168:171], v231 offset:19456
	ds_read_b128 v[172:175], v231 offset:20480
	ds_read_b128 v[184:187], v231 offset:21504
	ds_read_b128 v[188:191], v231 offset:22528
	ds_read_b128 v[192:195], v231 offset:23552
	global_load_lds_dwordx4 v[212:213], off
	v_lshl_add_u64 v[214:215], s[90:91], 0, v[148:149]
	s_mov_b32 m0, s14
	s_nop 0
	global_load_lds_dwordx4 v[214:215], off
	s_barrier
	s_waitcnt lgkmcnt(0)
	s_waitcnt lgkmcnt(0)
	v_mfma_f32_16x16x32_bf16 v[62:65], v[130:133], v[156:159], v[62:65]
	v_mfma_f32_16x16x32_bf16 v[58:61], v[138:141], v[156:159], v[58:61]
	v_mfma_f32_16x16x32_bf16 v[46:49], v[130:133], v[164:167], v[46:49]
	v_mfma_f32_16x16x32_bf16 v[42:45], v[138:141], v[164:167], v[42:45]
	v_mfma_f32_16x16x32_bf16 v[30:33], v[130:133], v[172:175], v[30:33]
	v_mfma_f32_16x16x32_bf16 v[26:29], v[138:141], v[172:175], v[26:29]
	v_mfma_f32_16x16x32_bf16 v[14:17], v[130:133], v[188:191], v[14:17]
	v_mfma_f32_16x16x32_bf16 v[10:13], v[138:141], v[188:191], v[10:13]
	v_mfma_f32_16x16x32_bf16 v[62:65], v[134:137], v[160:163], v[62:65]
	v_mfma_f32_16x16x32_bf16 v[58:61], v[142:145], v[160:163], v[58:61]
	v_mfma_f32_16x16x32_bf16 v[46:49], v[134:137], v[168:171], v[46:49]
	v_mfma_f32_16x16x32_bf16 v[42:45], v[142:145], v[168:171], v[42:45]
	v_mfma_f32_16x16x32_bf16 v[30:33], v[134:137], v[184:187], v[30:33]
	v_mfma_f32_16x16x32_bf16 v[26:29], v[142:145], v[184:187], v[26:29]
	v_mfma_f32_16x16x32_bf16 v[14:17], v[134:137], v[192:195], v[14:17]
	v_mfma_f32_16x16x32_bf16 v[10:13], v[142:145], v[192:195], v[10:13]
	s_barrier
	s_add_u32 s6, s62, 0x40000
	s_addc_u32 s7, s63, 0
	s_add_i32 s33, s94, s11
	v_lshl_add_u64 v[130:131], s[6:7], 0, v[146:147]
	s_mov_b32 m0, s33
	s_nop 0
	global_load_lds_dwordx4 v[130:131], off
	v_lshl_add_u64 v[130:131], s[6:7], 0, v[148:149]
	s_add_i32 m0, s33, 0x2000
	s_nop 0
	global_load_lds_dwordx4 v[130:131], off
	s_waitcnt vmcnt(6)
	s_barrier
	v_mfma_f32_16x16x32_bf16 v[54:57], v[196:199], v[156:159], v[54:57]
	v_mfma_f32_16x16x32_bf16 v[50:53], v[204:207], v[156:159], v[50:53]
	v_mfma_f32_16x16x32_bf16 v[38:41], v[196:199], v[164:167], v[38:41]
	v_mfma_f32_16x16x32_bf16 v[34:37], v[204:207], v[164:167], v[34:37]
	v_mfma_f32_16x16x32_bf16 v[22:25], v[196:199], v[172:175], v[22:25]
	v_mfma_f32_16x16x32_bf16 v[18:21], v[204:207], v[172:175], v[18:21]
	v_mfma_f32_16x16x32_bf16 v[6:9], v[196:199], v[188:191], v[6:9]
	v_mfma_f32_16x16x32_bf16 v[2:5], v[204:207], v[188:191], v[2:5]
	v_mfma_f32_16x16x32_bf16 v[54:57], v[200:203], v[160:163], v[54:57]
	v_mfma_f32_16x16x32_bf16 v[50:53], v[208:211], v[160:163], v[50:53]
	v_mfma_f32_16x16x32_bf16 v[38:41], v[200:203], v[168:171], v[38:41]
	v_mfma_f32_16x16x32_bf16 v[34:37], v[208:211], v[168:171], v[34:37]
	v_mfma_f32_16x16x32_bf16 v[22:25], v[200:203], v[184:187], v[22:25]
	v_mfma_f32_16x16x32_bf16 v[18:21], v[208:211], v[184:187], v[18:21]
	v_mfma_f32_16x16x32_bf16 v[6:9], v[200:203], v[192:195], v[6:9]
	v_mfma_f32_16x16x32_bf16 v[2:5], v[208:211], v[192:195], v[2:5]
	s_add_i32 s33, 0, 0x18000
	v_add_u32_e32 v0, s33, v155
	s_barrier
	ds_read_b128 v[130:133], v0
	ds_read_b128 v[134:137], v0 offset:1024
	ds_read_b128 v[138:141], v0 offset:2048
	ds_read_b128 v[142:145], v0 offset:3072
	s_add_u32 s6, s90, 0x40000
	s_addc_u32 s7, s91, 0
	s_mov_b32 m0, s15
	v_lshl_add_u64 v[196:197], s[6:7], 0, v[146:147]
	ds_read_b128 v[156:159], v231 offset:32768
	ds_read_b128 v[160:163], v231 offset:33792
	ds_read_b128 v[164:167], v231 offset:34816
	ds_read_b128 v[168:171], v231 offset:35840
	ds_read_b128 v[172:175], v231 offset:36864
	ds_read_b128 v[184:187], v231 offset:37888
	ds_read_b128 v[188:191], v231 offset:38912
	ds_read_b128 v[192:195], v231 offset:39936
	global_load_lds_dwordx4 v[196:197], off
	v_lshl_add_u64 v[196:197], s[6:7], 0, v[148:149]
	s_mov_b32 m0, s16
	s_nop 0
	global_load_lds_dwordx4 v[196:197], off
	s_waitcnt lgkmcnt(8)
	s_barrier
	s_waitcnt lgkmcnt(0)
	s_waitcnt lgkmcnt(0)
	v_mfma_f32_16x16x32_bf16 v[126:129], v[130:133], v[156:159], v[126:129]
	v_mfma_f32_16x16x32_bf16 v[122:125], v[138:141], v[156:159], v[122:125]
	v_mfma_f32_16x16x32_bf16 v[110:113], v[130:133], v[164:167], v[110:113]
	v_mfma_f32_16x16x32_bf16 v[106:109], v[138:141], v[164:167], v[106:109]
	v_mfma_f32_16x16x32_bf16 v[94:97], v[130:133], v[172:175], v[94:97]
	v_mfma_f32_16x16x32_bf16 v[90:93], v[138:141], v[172:175], v[90:93]
	v_mfma_f32_16x16x32_bf16 v[78:81], v[130:133], v[188:191], v[78:81]
	v_mfma_f32_16x16x32_bf16 v[74:77], v[138:141], v[188:191], v[74:77]
	v_mfma_f32_16x16x32_bf16 v[126:129], v[134:137], v[160:163], v[126:129]
	v_mfma_f32_16x16x32_bf16 v[122:125], v[142:145], v[160:163], v[122:125]
	v_mfma_f32_16x16x32_bf16 v[110:113], v[134:137], v[168:171], v[110:113]
	v_mfma_f32_16x16x32_bf16 v[106:109], v[142:145], v[168:171], v[106:109]
	v_mfma_f32_16x16x32_bf16 v[94:97], v[134:137], v[184:187], v[94:97]
	v_mfma_f32_16x16x32_bf16 v[90:93], v[142:145], v[184:187], v[90:93]
	v_mfma_f32_16x16x32_bf16 v[78:81], v[134:137], v[192:195], v[78:81]
	v_mfma_f32_16x16x32_bf16 v[74:77], v[142:145], v[192:195], v[74:77]
	s_barrier
	s_add_i32 s90, 0, 0x1c000
	s_add_i32 s6, s33, s11
	v_add_u32_e32 v0, s90, v155
	v_lshl_add_u64 v[176:177], v[176:177], 0, s[24:25]
	s_mov_b32 m0, s6
	ds_read_b128 v[196:199], v0
	ds_read_b128 v[200:203], v0 offset:1024
	ds_read_b128 v[204:207], v0 offset:2048
	ds_read_b128 v[208:211], v0 offset:3072
	global_load_lds_dwordx4 v[176:177], off
	v_lshl_add_u64 v[176:177], v[180:181], 0, s[24:25]
	s_add_i32 m0, s6, 0x2000
	s_nop 0
	global_load_lds_dwordx4 v[176:177], off
	s_barrier
	s_waitcnt lgkmcnt(0)
	s_waitcnt lgkmcnt(0)
	v_mfma_f32_16x16x32_bf16 v[118:121], v[196:199], v[156:159], v[118:121]
	v_mfma_f32_16x16x32_bf16 v[114:117], v[204:207], v[156:159], v[114:117]
	v_mfma_f32_16x16x32_bf16 v[102:105], v[196:199], v[164:167], v[102:105]
	v_mfma_f32_16x16x32_bf16 v[98:101], v[204:207], v[164:167], v[98:101]
	v_mfma_f32_16x16x32_bf16 v[86:89], v[196:199], v[172:175], v[86:89]
	v_mfma_f32_16x16x32_bf16 v[82:85], v[204:207], v[172:175], v[82:85]
	v_mfma_f32_16x16x32_bf16 v[70:73], v[196:199], v[188:191], v[70:73]
	v_mfma_f32_16x16x32_bf16 v[66:69], v[204:207], v[188:191], v[66:69]
	v_mfma_f32_16x16x32_bf16 v[118:121], v[200:203], v[160:163], v[118:121]
	v_mfma_f32_16x16x32_bf16 v[114:117], v[208:211], v[160:163], v[114:117]
	v_mfma_f32_16x16x32_bf16 v[102:105], v[200:203], v[168:171], v[102:105]
	v_mfma_f32_16x16x32_bf16 v[98:101], v[208:211], v[168:171], v[98:101]
	v_mfma_f32_16x16x32_bf16 v[86:89], v[200:203], v[184:187], v[86:89]
	v_mfma_f32_16x16x32_bf16 v[82:85], v[208:211], v[184:187], v[82:85]
	v_mfma_f32_16x16x32_bf16 v[70:73], v[200:203], v[192:195], v[70:73]
	v_mfma_f32_16x16x32_bf16 v[66:69], v[208:211], v[192:195], v[66:69]
	s_mov_b32 m0, s18
	v_lshl_add_u64 v[176:177], v[212:213], 0, s[24:25]
	s_barrier
	ds_read_b128 v[156:159], v231 offset:49152
	ds_read_b128 v[160:163], v231 offset:50176
	ds_read_b128 v[164:167], v231 offset:51200
	ds_read_b128 v[168:171], v231 offset:52224
	ds_read_b128 v[172:175], v231 offset:53248
	ds_read_b128 v[184:187], v231 offset:54272
	ds_read_b128 v[188:191], v231 offset:55296
	ds_read_b128 v[192:195], v231 offset:56320
	global_load_lds_dwordx4 v[176:177], off
	v_lshl_add_u64 v[176:177], v[214:215], 0, s[24:25]
	s_mov_b32 m0, s19
	s_nop 0
	global_load_lds_dwordx4 v[176:177], off
	s_barrier
	s_waitcnt lgkmcnt(0)
	s_waitcnt lgkmcnt(0)
	v_mfma_f32_16x16x32_bf16 v[62:65], v[130:133], v[156:159], v[62:65]
	v_mfma_f32_16x16x32_bf16 v[58:61], v[138:141], v[156:159], v[58:61]
	v_mfma_f32_16x16x32_bf16 v[46:49], v[130:133], v[164:167], v[46:49]
	v_mfma_f32_16x16x32_bf16 v[42:45], v[138:141], v[164:167], v[42:45]
	v_mfma_f32_16x16x32_bf16 v[30:33], v[130:133], v[172:175], v[30:33]
	v_mfma_f32_16x16x32_bf16 v[26:29], v[138:141], v[172:175], v[26:29]
	v_mfma_f32_16x16x32_bf16 v[14:17], v[130:133], v[188:191], v[14:17]
	v_mfma_f32_16x16x32_bf16 v[10:13], v[138:141], v[188:191], v[10:13]
	v_mfma_f32_16x16x32_bf16 v[62:65], v[134:137], v[160:163], v[62:65]
	v_mfma_f32_16x16x32_bf16 v[58:61], v[142:145], v[160:163], v[58:61]
	v_mfma_f32_16x16x32_bf16 v[46:49], v[134:137], v[168:171], v[46:49]
	v_mfma_f32_16x16x32_bf16 v[42:45], v[142:145], v[168:171], v[42:45]
	v_mfma_f32_16x16x32_bf16 v[30:33], v[134:137], v[184:187], v[30:33]
	v_mfma_f32_16x16x32_bf16 v[26:29], v[142:145], v[184:187], v[26:29]
	v_mfma_f32_16x16x32_bf16 v[14:17], v[134:137], v[192:195], v[14:17]
	v_mfma_f32_16x16x32_bf16 v[10:13], v[142:145], v[192:195], v[10:13]
	s_barrier
	s_add_u32 s6, s62, 0x40080
	s_addc_u32 s7, s63, 0
	s_add_i32 s33, s90, s11
	v_lshl_add_u64 v[130:131], s[6:7], 0, v[146:147]
	s_mov_b32 m0, s33
	s_nop 0
	global_load_lds_dwordx4 v[130:131], off
	v_lshl_add_u64 v[130:131], s[6:7], 0, v[148:149]
	s_add_i32 m0, s33, 0x2000
	s_nop 0
	global_load_lds_dwordx4 v[130:131], off
	s_waitcnt vmcnt(6)
	s_barrier
	v_mfma_f32_16x16x32_bf16 v[54:57], v[196:199], v[156:159], v[54:57]
	v_mfma_f32_16x16x32_bf16 v[50:53], v[204:207], v[156:159], v[50:53]
	v_mfma_f32_16x16x32_bf16 v[38:41], v[196:199], v[164:167], v[38:41]
	v_mfma_f32_16x16x32_bf16 v[34:37], v[204:207], v[164:167], v[34:37]
	v_mfma_f32_16x16x32_bf16 v[22:25], v[196:199], v[172:175], v[22:25]
	v_mfma_f32_16x16x32_bf16 v[18:21], v[204:207], v[172:175], v[18:21]
	v_mfma_f32_16x16x32_bf16 v[6:9], v[196:199], v[188:191], v[6:9]
	v_mfma_f32_16x16x32_bf16 v[2:5], v[204:207], v[188:191], v[2:5]
	v_mfma_f32_16x16x32_bf16 v[54:57], v[200:203], v[160:163], v[54:57]
	v_mfma_f32_16x16x32_bf16 v[50:53], v[208:211], v[160:163], v[50:53]
	v_mfma_f32_16x16x32_bf16 v[38:41], v[200:203], v[168:171], v[38:41]
	v_mfma_f32_16x16x32_bf16 v[34:37], v[208:211], v[168:171], v[34:37]
	v_mfma_f32_16x16x32_bf16 v[22:25], v[200:203], v[184:187], v[22:25]
	v_mfma_f32_16x16x32_bf16 v[18:21], v[208:211], v[184:187], v[18:21]
	v_mfma_f32_16x16x32_bf16 v[6:9], v[200:203], v[192:195], v[6:9]
	v_mfma_f32_16x16x32_bf16 v[2:5], v[208:211], v[192:195], v[2:5]
	s_add_i32 vcc_hi, vcc_hi, 2
	s_add_u32 s2, s2, 0x100
	s_addc_u32 s3, s3, 0
	s_add_u32 s69, s69, 0x100
	s_addc_u32 vcc_lo, vcc_lo, 0
	s_cmp_gt_u32 vcc_hi, 13
	s_barrier
	s_cbranch_scc0 .LBB0_179
	s_setprio 0
	s_cmp_gt_i32 s72, 17
	s_cbranch_scc0 .LBB0_182
	s_and_b32 s1, s72, 0x7ffffffe
	s_cmp_gt_u32 s72, 25
	s_cselect_b32 s2, 3, 0
	s_cmp_lg_u32 s1, 22
	s_cselect_b32 s1, s2, 4
	s_cmp_eq_u32 s72, 19
	s_cselect_b64 vcc, -1, 0
	v_mov_b32_e32 v0, 0x3e000000
	s_and_b64 s[2:3], vcc, exec
	v_cndmask_b32_e32 v154, 1.0, v0, vcc
	s_cselect_b32 s39, 2, s1
	s_movk_i32 s94, 0x2000
	s_mov_b32 s1, 0
	s_cbranch_execz .LBB0_183
	s_branch .LBB0_188

.LBB0_519:
	s_lshl_b32 s0, s28, 26
	s_add_u32 s0, s18, s0
	s_addc_u32 s1, s19, 0
	s_add_u32 s0, s0, 0x3c00000
	v_lshrrev_b32_e32 v17, 1, v13
	s_addc_u32 s1, s1, 0
	v_and_b32_e32 v17, 24, v17
	s_add_u32 s40, s18, 0x19c00000
	v_and_b32_e32 v16, 15, v13
	v_lshlrev_b32_e32 v18, 1, v17
	v_lshlrev_b32_e32 v13, 2, v13
	s_addc_u32 s41, s19, 0
	s_and_b32 s6, s20, 3
	v_lshl_or_b32 v179, s21, 6, v16
	v_lshl_or_b32 v16, v16, 6, v18
	s_lshl_b32 s7, s21, 13
	v_and_b32_e32 v13, 32, v13
	v_bitop3_b32 v18, v16, s7, v13 bitop3:0xde
	s_lshl_b32 s7, s6, 12
	s_add_i32 m0, s3, 0x18000
	v_lshl_add_u64 v[8:9], v[8:9], 0, s[24:25]
	v_bitop3_b32 v184, v16, s7, v13 bitop3:0xde
	s_waitcnt vmcnt(4)
	s_barrier
	global_load_lds_dwordx4 v[8:9], off
	v_lshl_add_u64 v[6:7], v[6:7], 0, s[24:25]
	s_add_i32 m0, s3, 0x1a000
	s_add_i32 s7, s3, 0x8000
	s_add_i32 s18, s3, 0xa000
	global_load_lds_dwordx4 v[6:7], off
	v_lshl_add_u64 v[4:5], v[4:5], 0, s[24:25]
	s_mov_b32 m0, s7
	s_add_u32 s20, s90, 0x20080
	global_load_lds_dwordx4 v[4:5], off
	v_lshl_add_u64 v[2:3], v[2:3], 0, s[24:25]
	s_mov_b32 m0, s18
	s_addc_u32 s21, s91, 0
	global_load_lds_dwordx4 v[2:3], off
	s_add_i32 m0, s3, 0x1c000
	v_lshl_add_u64 v[2:3], s[20:21], 0, v[162:163]
	global_load_lds_dwordx4 v[2:3], off
	v_lshl_add_u64 v[2:3], s[20:21], 0, v[164:165]
	s_add_i32 m0, s3, 0x1e000
	v_or_b32_e32 v186, 16, v179
	global_load_lds_dwordx4 v[2:3], off
	v_lshlrev_b32_e32 v2, 8, v179
	v_and_b32_e32 v185, 0xcf00, v2
	v_lshlrev_b32_e32 v2, 8, v186
	v_or_b32_e32 v188, 32, v179
	v_and_b32_e32 v187, 0xdf00, v2
	v_lshlrev_b32_e32 v2, 8, v188
	v_or_b32_e32 v190, 48, v179
	v_and_b32_e32 v189, 0xef00, v2
	v_lshlrev_b32_e32 v2, 8, v190
	v_add_u32_e32 v192, 0x80, v179
	v_and_b32_e32 v191, 0xff00, v2
	v_lshlrev_b32_e32 v2, 8, v192
	v_add_u32_e32 v194, 0x90, v179
	v_and_b32_e32 v193, 0xcf00, v2
	v_lshlrev_b32_e32 v2, 8, v194
	v_add_u32_e32 v196, 0xa0, v179
	v_and_b32_e32 v195, 0xdf00, v2
	v_lshlrev_b32_e32 v2, 8, v196
	v_add_u32_e32 v198, 0xb0, v179
	v_and_b32_e32 v197, 0xef00, v2
	v_lshlrev_b32_e32 v2, 8, v198
	v_and_b32_e32 v199, 0xff00, v2
	v_lshlrev_b32_e32 v2, 13, v0
	v_and_b32_e32 v2, 0xffffc000, v2
	v_lshl_add_u32 v2, v10, 10, v2
	v_and_b32_e32 v0, 1, v0
	v_lshl_or_b32 v0, v0, 6, v2
	v_lshl_add_u32 v166, v11, 1, v0
	v_lshlrev_b32_e32 v0, 13, v12
	v_and_b32_e32 v0, 0xffffc000, v0
	s_waitcnt vmcnt(6)
	v_lshl_add_u32 v0, v14, 10, v0
	v_and_b32_e32 v2, 1, v12
	v_lshl_or_b32 v0, v2, 6, v0
	s_ashr_i32 s19, s8, 31
	v_lshl_or_b32 v200, s6, 6, v17
	v_mov_b32_e32 v167, v1
	v_lshl_add_u32 v168, v15, 1, v0
	v_mov_b32_e32 v169, v1
	s_mov_b32 s20, 0
	v_add_u32_e32 v201, 0, v18
	s_barrier
	s_branch .LBB0_521
	s_nop 0
	s_nop 0
	s_nop 0
	s_nop 0
	s_nop 0
	s_nop 0
	s_nop 0
.LBB0_520:
	s_waitcnt vmcnt(0)
	v_lshlrev_b32_e32 v68, 16, v62
	v_and_b32_e32 v69, 0xffff0000, v62
	v_lshlrev_b32_e32 v62, 16, v63
	v_and_b32_e32 v63, 0xffff0000, v63
	v_pk_mul_f32 v[68:69], v[174:175], v[68:69]
	v_lshlrev_b32_e32 v70, 16, v58
	v_and_b32_e32 v71, 0xffff0000, v58
	v_pk_mul_f32 v[62:63], v[174:175], v[62:63]
	v_lshlrev_b32_e32 v58, 16, v59
	v_and_b32_e32 v59, 0xffff0000, v59
	v_pk_fma_f32 v[30:31], v[30:31], v[70:71], v[68:69]
	v_pk_fma_f32 v[32:33], v[32:33], v[58:59], v[62:63]
	v_cvt_pk_bf16_f32 v30, v30, v31
	v_cvt_pk_bf16_f32 v31, v32, v33
	v_lshlrev_b32_e32 v32, 16, v64
	v_and_b32_e32 v33, 0xffff0000, v64
	v_pk_mul_f32 v[32:33], v[174:175], v[32:33]
	v_lshlrev_b32_e32 v58, 16, v60
	v_and_b32_e32 v59, 0xffff0000, v60
	v_pk_fma_f32 v[26:27], v[26:27], v[58:59], v[32:33]
	v_lshlrev_b32_e32 v58, 16, v61
	v_cvt_pk_bf16_f32 v32, v26, v27
	v_lshlrev_b32_e32 v26, 16, v65
	v_and_b32_e32 v27, 0xffff0000, v65
	v_pk_mul_f32 v[26:27], v[174:175], v[26:27]
	v_and_b32_e32 v59, 0xffff0000, v61
	v_pk_fma_f32 v[26:27], v[28:29], v[58:59], v[26:27]
	v_lshlrev_b32_e32 v28, 16, v46
	v_cvt_pk_bf16_f32 v33, v26, v27
	v_lshlrev_b32_e32 v26, 16, v50
	v_and_b32_e32 v27, 0xffff0000, v50
	v_pk_mul_f32 v[26:27], v[174:175], v[26:27]
	v_and_b32_e32 v29, 0xffff0000, v46
	v_pk_fma_f32 v[22:23], v[22:23], v[28:29], v[26:27]
	v_lshlrev_b32_e32 v26, 16, v51
	v_and_b32_e32 v27, 0xffff0000, v51
	v_pk_mul_f32 v[26:27], v[174:175], v[26:27]
	v_lshlrev_b32_e32 v28, 16, v47
	v_and_b32_e32 v29, 0xffff0000, v47
	v_pk_fma_f32 v[24:25], v[24:25], v[28:29], v[26:27]
	v_cvt_pk_bf16_f32 v22, v22, v23
	v_cvt_pk_bf16_f32 v23, v24, v25
	v_lshlrev_b32_e32 v24, 16, v52
	v_and_b32_e32 v25, 0xffff0000, v52
	v_pk_mul_f32 v[24:25], v[174:175], v[24:25]
	v_lshlrev_b32_e32 v26, 16, v48
	v_and_b32_e32 v27, 0xffff0000, v48
	v_add_u32_e32 v66, 0xa0, v170
	v_pk_fma_f32 v[18:19], v[18:19], v[26:27], v[24:25]
	v_ashrrev_i32_e32 v67, 31, v66
	v_cvt_pk_bf16_f32 v24, v18, v19
	v_lshlrev_b32_e32 v18, 16, v53
	v_and_b32_e32 v19, 0xffff0000, v53
	v_lshlrev_b64 v[66:67], 11, v[66:67]
	v_pk_mul_f32 v[18:19], v[174:175], v[18:19]
	v_lshlrev_b32_e32 v26, 16, v49
	v_and_b32_e32 v27, 0xffff0000, v49
	v_lshl_add_u64 v[66:67], s[0:1], 0, v[66:67]
	v_mov_b32_e32 v173, v1
	v_pk_fma_f32 v[18:19], v[20:21], v[26:27], v[18:19]
	v_lshl_add_u64 v[66:67], v[66:67], 0, v[172:173]
	v_cvt_pk_bf16_f32 v25, v18, v19
	v_lshlrev_b32_e32 v20, 16, v54
	v_and_b32_e32 v21, 0xffff0000, v54
	global_store_dwordx4 v[66:67], v[22:25], off offset:64
	v_pk_mul_f32 v[20:21], v[174:175], v[20:21]
	v_add_u32_e32 v18, 0xb0, v170
	v_lshlrev_b32_e32 v22, 16, v42
	v_and_b32_e32 v23, 0xffff0000, v42
	v_pk_fma_f32 v[14:15], v[14:15], v[22:23], v[20:21]
	v_lshlrev_b32_e32 v20, 16, v55
	v_and_b32_e32 v21, 0xffff0000, v55
	v_pk_mul_f32 v[20:21], v[174:175], v[20:21]
	v_lshlrev_b32_e32 v22, 16, v43
	v_and_b32_e32 v23, 0xffff0000, v43
	v_pk_fma_f32 v[16:17], v[16:17], v[22:23], v[20:21]
	v_cvt_pk_bf16_f32 v14, v14, v15
	v_cvt_pk_bf16_f32 v15, v16, v17
	v_lshlrev_b32_e32 v16, 16, v56
	v_and_b32_e32 v17, 0xffff0000, v56
	v_pk_mul_f32 v[16:17], v[174:175], v[16:17]
	v_lshlrev_b32_e32 v20, 16, v44
	v_and_b32_e32 v21, 0xffff0000, v44
	v_pk_fma_f32 v[10:11], v[10:11], v[20:21], v[16:17]
	v_lshlrev_b32_e32 v20, 16, v45
	v_cvt_pk_bf16_f32 v16, v10, v11
	v_lshlrev_b32_e32 v10, 16, v57
	v_and_b32_e32 v11, 0xffff0000, v57
	v_pk_mul_f32 v[10:11], v[174:175], v[10:11]
	v_and_b32_e32 v21, 0xffff0000, v45
	v_pk_fma_f32 v[10:11], v[12:13], v[20:21], v[10:11]
	v_lshlrev_b32_e32 v12, 16, v38
	v_cvt_pk_bf16_f32 v17, v10, v11
	v_lshlrev_b32_e32 v10, 16, v34
	v_and_b32_e32 v11, 0xffff0000, v34
	v_pk_mul_f32 v[10:11], v[174:175], v[10:11]
	v_and_b32_e32 v13, 0xffff0000, v38
	v_pk_fma_f32 v[6:7], v[6:7], v[12:13], v[10:11]
	v_lshlrev_b32_e32 v10, 16, v35
	v_and_b32_e32 v11, 0xffff0000, v35
	v_pk_mul_f32 v[10:11], v[174:175], v[10:11]
	v_lshlrev_b32_e32 v12, 16, v39
	v_and_b32_e32 v13, 0xffff0000, v39
	v_pk_fma_f32 v[8:9], v[8:9], v[12:13], v[10:11]
	v_cvt_pk_bf16_f32 v6, v6, v7
	v_cvt_pk_bf16_f32 v7, v8, v9
	v_lshlrev_b32_e32 v8, 16, v36
	v_and_b32_e32 v9, 0xffff0000, v36
	v_pk_mul_f32 v[8:9], v[174:175], v[8:9]
	v_lshlrev_b32_e32 v10, 16, v40
	v_and_b32_e32 v11, 0xffff0000, v40
	v_pk_fma_f32 v[2:3], v[2:3], v[10:11], v[8:9]
	v_ashrrev_i32_e32 v19, 31, v18
	v_cvt_pk_bf16_f32 v8, v2, v3
	v_lshlrev_b32_e32 v2, 16, v37
	v_and_b32_e32 v3, 0xffff0000, v37
	v_lshlrev_b64 v[18:19], 11, v[18:19]
	v_pk_mul_f32 v[2:3], v[174:175], v[2:3]
	v_lshlrev_b32_e32 v10, 16, v41
	v_and_b32_e32 v11, 0xffff0000, v41
	v_lshl_add_u64 v[18:19], s[0:1], 0, v[18:19]
	v_pk_fma_f32 v[2:3], v[4:5], v[10:11], v[2:3]
	v_lshl_add_u64 v[18:19], v[18:19], 0, v[172:173]
	v_cvt_pk_bf16_f32 v9, v2, v3
	s_and_b64 vcc, exec, s[36:37]
	s_mov_b32 s38, s68
	s_mov_b32 s2, s46
	s_mov_b64 s[90:91], s[88:89]
	s_mov_b64 s[62:63], s[84:85]
	global_store_dwordx4 v[66:67], v[30:33], off
	global_store_dwordx4 v[18:19], v[14:17], off
	global_store_dwordx4 v[18:19], v[6:9], off offset:64
	s_cbranch_vccnz .LBB0_545

.LBB0_528:
	s_cmp_ge_u32 s3, 0x1000
	s_cbranch_scc0 .Lsp_2
	s_setprio 1
.Lsp_2:
	s_add_u32 s6, s62, 0xfffe0080
	s_addc_u32 s33, s63, -1
	s_add_i32 s72, 0, 0x10000
	v_add_u32_e32 v0, s72, v184
	ds_read_b128 v[130:133], v0
	ds_read_b128 v[134:137], v0 offset:1024
	ds_read_b128 v[138:141], v0 offset:2048
	ds_read_b128 v[142:145], v0 offset:3072
	s_cmp_eq_u32 s69, 4
	s_cselect_b32 vcc_hi, s21, s33
	s_cselect_b32 vcc_lo, s22, s6
	s_cselect_b32 s91, s23, s48
	s_cselect_b32 s90, s39, s47
	v_lshl_add_u64 v[180:181], s[62:63], 0, v[166:167]
	s_add_i32 m0, s3, 0xc000
	ds_read_b128 v[146:149], v201
	ds_read_b128 v[150:153], v201 offset:1024
	ds_read_b128 v[154:157], v201 offset:2048
	ds_read_b128 v[158:161], v201 offset:3072
	ds_read_b128 v[170:173], v201 offset:4096
	ds_read_b128 v[174:177], v201 offset:5120
	ds_read_b128 v[202:205], v201 offset:6144
	ds_read_b128 v[206:209], v201 offset:7168
	global_load_lds_dwordx4 v[180:181], off
	v_lshl_add_u64 v[180:181], s[62:63], 0, v[168:169]
	s_add_i32 m0, s3, 0xe000
	s_nop 0
	global_load_lds_dwordx4 v[180:181], off
	s_waitcnt lgkmcnt(8)
	s_barrier
	s_waitcnt lgkmcnt(0)
	s_waitcnt lgkmcnt(0)
	v_mfma_f32_16x16x32_bf16 v[126:129], v[130:133], v[146:149], v[126:129]
	v_mfma_f32_16x16x32_bf16 v[122:125], v[138:141], v[146:149], v[122:125]
	v_mfma_f32_16x16x32_bf16 v[110:113], v[130:133], v[154:157], v[110:113]
	v_mfma_f32_16x16x32_bf16 v[106:109], v[138:141], v[154:157], v[106:109]
	v_mfma_f32_16x16x32_bf16 v[94:97], v[130:133], v[170:173], v[94:97]
	v_mfma_f32_16x16x32_bf16 v[90:93], v[138:141], v[170:173], v[90:93]
	v_mfma_f32_16x16x32_bf16 v[78:81], v[130:133], v[202:205], v[78:81]
	v_mfma_f32_16x16x32_bf16 v[74:77], v[138:141], v[202:205], v[74:77]
	v_mfma_f32_16x16x32_bf16 v[126:129], v[134:137], v[150:153], v[126:129]
	v_mfma_f32_16x16x32_bf16 v[122:125], v[142:145], v[150:153], v[122:125]
	v_mfma_f32_16x16x32_bf16 v[110:113], v[134:137], v[158:161], v[110:113]
	v_mfma_f32_16x16x32_bf16 v[106:109], v[142:145], v[158:161], v[106:109]
	v_mfma_f32_16x16x32_bf16 v[94:97], v[134:137], v[174:177], v[94:97]
	v_mfma_f32_16x16x32_bf16 v[90:93], v[142:145], v[174:177], v[90:93]
	v_mfma_f32_16x16x32_bf16 v[78:81], v[134:137], v[206:209], v[78:81]
	v_mfma_f32_16x16x32_bf16 v[74:77], v[142:145], v[206:209], v[74:77]
	s_barrier
	s_add_i32 s6, 0, 0x14000
	s_add_i32 s33, s72, s14
	v_add_u32_e32 v0, s6, v184
	v_lshl_add_u64 v[180:181], s[90:91], 0, v[162:163]
	s_mov_b32 m0, s33
	ds_read_b128 v[210:213], v0
	ds_read_b128 v[214:217], v0 offset:1024
	ds_read_b128 v[218:221], v0 offset:2048
	ds_read_b128 v[222:225], v0 offset:3072
	global_load_lds_dwordx4 v[180:181], off
	v_lshl_add_u64 v[226:227], s[90:91], 0, v[164:165]
	s_add_i32 m0, s33, 0x2000
	s_nop 0
	global_load_lds_dwordx4 v[226:227], off
	s_barrier
	s_waitcnt lgkmcnt(0)
	s_waitcnt lgkmcnt(0)
	v_mfma_f32_16x16x32_bf16 v[118:121], v[210:213], v[146:149], v[118:121]
	v_mfma_f32_16x16x32_bf16 v[114:117], v[218:221], v[146:149], v[114:117]
	v_mfma_f32_16x16x32_bf16 v[102:105], v[210:213], v[154:157], v[102:105]
	v_mfma_f32_16x16x32_bf16 v[98:101], v[218:221], v[154:157], v[98:101]
	v_mfma_f32_16x16x32_bf16 v[86:89], v[210:213], v[170:173], v[86:89]
	v_mfma_f32_16x16x32_bf16 v[82:85], v[218:221], v[170:173], v[82:85]
	v_mfma_f32_16x16x32_bf16 v[70:73], v[210:213], v[202:205], v[70:73]
	v_mfma_f32_16x16x32_bf16 v[66:69], v[218:221], v[202:205], v[66:69]
	v_mfma_f32_16x16x32_bf16 v[118:121], v[214:217], v[150:153], v[118:121]
	v_mfma_f32_16x16x32_bf16 v[114:117], v[222:225], v[150:153], v[114:117]
	v_mfma_f32_16x16x32_bf16 v[102:105], v[214:217], v[158:161], v[102:105]
	v_mfma_f32_16x16x32_bf16 v[98:101], v[222:225], v[158:161], v[98:101]
	v_mfma_f32_16x16x32_bf16 v[86:89], v[214:217], v[174:177], v[86:89]
	v_mfma_f32_16x16x32_bf16 v[82:85], v[222:225], v[174:177], v[82:85]
	v_mfma_f32_16x16x32_bf16 v[70:73], v[214:217], v[206:209], v[70:73]
	v_mfma_f32_16x16x32_bf16 v[66:69], v[222:225], v[206:209], v[66:69]
	s_mov_b32 m0, s3
	v_lshl_add_u64 v[240:241], vcc, 0, v[162:163]
	s_barrier
	ds_read_b128 v[146:149], v201 offset:16384
	ds_read_b128 v[150:153], v201 offset:17408
	ds_read_b128 v[154:157], v201 offset:18432
	ds_read_b128 v[158:161], v201 offset:19456
	ds_read_b128 v[170:173], v201 offset:20480
	ds_read_b128 v[174:177], v201 offset:21504
	ds_read_b128 v[202:205], v201 offset:22528
	ds_read_b128 v[206:209], v201 offset:23552
	global_load_lds_dwordx4 v[240:241], off
	v_lshl_add_u64 v[244:245], vcc, 0, v[164:165]
	s_mov_b32 m0, s15
	s_nop 0
	global_load_lds_dwordx4 v[244:245], off
	s_barrier
	s_waitcnt lgkmcnt(0)
	s_waitcnt lgkmcnt(0)
	v_mfma_f32_16x16x32_bf16 v[62:65], v[130:133], v[146:149], v[62:65]
	v_mfma_f32_16x16x32_bf16 v[58:61], v[138:141], v[146:149], v[58:61]
	v_mfma_f32_16x16x32_bf16 v[46:49], v[130:133], v[154:157], v[46:49]
	v_mfma_f32_16x16x32_bf16 v[42:45], v[138:141], v[154:157], v[42:45]
	v_mfma_f32_16x16x32_bf16 v[30:33], v[130:133], v[170:173], v[30:33]
	v_mfma_f32_16x16x32_bf16 v[26:29], v[138:141], v[170:173], v[26:29]
	v_mfma_f32_16x16x32_bf16 v[14:17], v[130:133], v[202:205], v[14:17]
	v_mfma_f32_16x16x32_bf16 v[10:13], v[138:141], v[202:205], v[10:13]
	v_mfma_f32_16x16x32_bf16 v[62:65], v[134:137], v[150:153], v[62:65]
	v_mfma_f32_16x16x32_bf16 v[58:61], v[142:145], v[150:153], v[58:61]
	v_mfma_f32_16x16x32_bf16 v[46:49], v[134:137], v[158:161], v[46:49]
	v_mfma_f32_16x16x32_bf16 v[42:45], v[142:145], v[158:161], v[42:45]
	v_mfma_f32_16x16x32_bf16 v[30:33], v[134:137], v[174:177], v[30:33]
	v_mfma_f32_16x16x32_bf16 v[26:29], v[142:145], v[174:177], v[26:29]
	v_mfma_f32_16x16x32_bf16 v[14:17], v[134:137], v[206:209], v[14:17]
	v_mfma_f32_16x16x32_bf16 v[10:13], v[142:145], v[206:209], v[10:13]
	s_barrier
	s_add_u32 s72, s90, 0x20000
	s_addc_u32 s73, s91, 0
	s_add_i32 s6, s6, s14
	v_lshl_add_u64 v[130:131], s[72:73], 0, v[162:163]
	s_mov_b32 m0, s6
	s_nop 0
	global_load_lds_dwordx4 v[130:131], off
	v_lshl_add_u64 v[130:131], s[72:73], 0, v[164:165]
	s_add_i32 m0, s6, 0x2000
	s_nop 0
	global_load_lds_dwordx4 v[130:131], off
	s_waitcnt vmcnt(6)
	s_barrier
	v_mfma_f32_16x16x32_bf16 v[54:57], v[210:213], v[146:149], v[54:57]
	v_mfma_f32_16x16x32_bf16 v[50:53], v[218:221], v[146:149], v[50:53]
	v_mfma_f32_16x16x32_bf16 v[38:41], v[210:213], v[154:157], v[38:41]
	v_mfma_f32_16x16x32_bf16 v[34:37], v[218:221], v[154:157], v[34:37]
	v_mfma_f32_16x16x32_bf16 v[22:25], v[210:213], v[170:173], v[22:25]
	v_mfma_f32_16x16x32_bf16 v[18:21], v[218:221], v[170:173], v[18:21]
	v_mfma_f32_16x16x32_bf16 v[6:9], v[210:213], v[202:205], v[6:9]
	v_mfma_f32_16x16x32_bf16 v[2:5], v[218:221], v[202:205], v[2:5]
	v_mfma_f32_16x16x32_bf16 v[54:57], v[214:217], v[150:153], v[54:57]
	v_mfma_f32_16x16x32_bf16 v[50:53], v[222:225], v[150:153], v[50:53]
	v_mfma_f32_16x16x32_bf16 v[38:41], v[214:217], v[158:161], v[38:41]
	v_mfma_f32_16x16x32_bf16 v[34:37], v[222:225], v[158:161], v[34:37]
	v_mfma_f32_16x16x32_bf16 v[22:25], v[214:217], v[174:177], v[22:25]
	v_mfma_f32_16x16x32_bf16 v[18:21], v[222:225], v[174:177], v[18:21]
	v_mfma_f32_16x16x32_bf16 v[6:9], v[214:217], v[206:209], v[6:9]
	v_mfma_f32_16x16x32_bf16 v[2:5], v[222:225], v[206:209], v[2:5]
	s_add_i32 s6, 0, 0x18000
	v_add_u32_e32 v0, s6, v184
	s_barrier
	ds_read_b128 v[130:133], v0
	ds_read_b128 v[134:137], v0 offset:1024
	ds_read_b128 v[138:141], v0 offset:2048
	ds_read_b128 v[142:145], v0 offset:3072
	s_add_u32 s72, vcc_lo, 0x20000
	s_addc_u32 s73, vcc_hi, 0
	s_mov_b32 m0, s16
	v_lshl_add_u64 v[210:211], s[72:73], 0, v[162:163]
	ds_read_b128 v[146:149], v201 offset:32768
	ds_read_b128 v[150:153], v201 offset:33792
	ds_read_b128 v[154:157], v201 offset:34816
	ds_read_b128 v[158:161], v201 offset:35840
	ds_read_b128 v[170:173], v201 offset:36864
	ds_read_b128 v[174:177], v201 offset:37888
	ds_read_b128 v[202:205], v201 offset:38912
	ds_read_b128 v[206:209], v201 offset:39936
	global_load_lds_dwordx4 v[210:211], off
	v_lshl_add_u64 v[210:211], s[72:73], 0, v[164:165]
	s_mov_b32 m0, s17
	s_nop 0
	global_load_lds_dwordx4 v[210:211], off
	s_waitcnt lgkmcnt(8)
	s_barrier
	s_waitcnt lgkmcnt(0)
	s_waitcnt lgkmcnt(0)
	v_mfma_f32_16x16x32_bf16 v[126:129], v[130:133], v[146:149], v[126:129]
	v_mfma_f32_16x16x32_bf16 v[122:125], v[138:141], v[146:149], v[122:125]
	v_mfma_f32_16x16x32_bf16 v[110:113], v[130:133], v[154:157], v[110:113]
	v_mfma_f32_16x16x32_bf16 v[106:109], v[138:141], v[154:157], v[106:109]
	v_mfma_f32_16x16x32_bf16 v[94:97], v[130:133], v[170:173], v[94:97]
	v_mfma_f32_16x16x32_bf16 v[90:93], v[138:141], v[170:173], v[90:93]
	v_mfma_f32_16x16x32_bf16 v[78:81], v[130:133], v[202:205], v[78:81]
	v_mfma_f32_16x16x32_bf16 v[74:77], v[138:141], v[202:205], v[74:77]
	v_mfma_f32_16x16x32_bf16 v[126:129], v[134:137], v[150:153], v[126:129]
	v_mfma_f32_16x16x32_bf16 v[122:125], v[142:145], v[150:153], v[122:125]
	v_mfma_f32_16x16x32_bf16 v[110:113], v[134:137], v[158:161], v[110:113]
	v_mfma_f32_16x16x32_bf16 v[106:109], v[142:145], v[158:161], v[106:109]
	v_mfma_f32_16x16x32_bf16 v[94:97], v[134:137], v[174:177], v[94:97]
	v_mfma_f32_16x16x32_bf16 v[90:93], v[142:145], v[174:177], v[90:93]
	v_mfma_f32_16x16x32_bf16 v[78:81], v[134:137], v[206:209], v[78:81]
	v_mfma_f32_16x16x32_bf16 v[74:77], v[142:145], v[206:209], v[74:77]
	s_barrier
	s_add_i32 s33, 0, 0x1c000
	s_add_i32 s6, s6, s14
	v_add_u32_e32 v0, s33, v184
	v_lshl_add_u64 v[180:181], v[180:181], 0, s[24:25]
	s_mov_b32 m0, s6
	ds_read_b128 v[210:213], v0
	ds_read_b128 v[214:217], v0 offset:1024
	ds_read_b128 v[218:221], v0 offset:2048
	ds_read_b128 v[222:225], v0 offset:3072
	global_load_lds_dwordx4 v[180:181], off
	v_lshl_add_u64 v[180:181], v[226:227], 0, s[24:25]
	s_add_i32 m0, s6, 0x2000
	s_nop 0
	global_load_lds_dwordx4 v[180:181], off
	s_barrier
	s_waitcnt lgkmcnt(0)
	s_waitcnt lgkmcnt(0)
	v_mfma_f32_16x16x32_bf16 v[118:121], v[210:213], v[146:149], v[118:121]
	v_mfma_f32_16x16x32_bf16 v[114:117], v[218:221], v[146:149], v[114:117]
	v_mfma_f32_16x16x32_bf16 v[102:105], v[210:213], v[154:157], v[102:105]
	v_mfma_f32_16x16x32_bf16 v[98:101], v[218:221], v[154:157], v[98:101]
	v_mfma_f32_16x16x32_bf16 v[86:89], v[210:213], v[170:173], v[86:89]
	v_mfma_f32_16x16x32_bf16 v[82:85], v[218:221], v[170:173], v[82:85]
	v_mfma_f32_16x16x32_bf16 v[70:73], v[210:213], v[202:205], v[70:73]
	v_mfma_f32_16x16x32_bf16 v[66:69], v[218:221], v[202:205], v[66:69]
	v_mfma_f32_16x16x32_bf16 v[118:121], v[214:217], v[150:153], v[118:121]
	v_mfma_f32_16x16x32_bf16 v[114:117], v[222:225], v[150:153], v[114:117]
	v_mfma_f32_16x16x32_bf16 v[102:105], v[214:217], v[158:161], v[102:105]
	v_mfma_f32_16x16x32_bf16 v[98:101], v[222:225], v[158:161], v[98:101]
	v_mfma_f32_16x16x32_bf16 v[86:89], v[214:217], v[174:177], v[86:89]
	v_mfma_f32_16x16x32_bf16 v[82:85], v[222:225], v[174:177], v[82:85]
	v_mfma_f32_16x16x32_bf16 v[70:73], v[214:217], v[206:209], v[70:73]
	v_mfma_f32_16x16x32_bf16 v[66:69], v[222:225], v[206:209], v[66:69]
	s_mov_b32 m0, s7
	v_lshl_add_u64 v[180:181], v[240:241], 0, s[24:25]
	s_barrier
	ds_read_b128 v[146:149], v201 offset:49152
	ds_read_b128 v[150:153], v201 offset:50176
	ds_read_b128 v[154:157], v201 offset:51200
	ds_read_b128 v[158:161], v201 offset:52224
	ds_read_b128 v[170:173], v201 offset:53248
	ds_read_b128 v[174:177], v201 offset:54272
	ds_read_b128 v[202:205], v201 offset:55296
	ds_read_b128 v[206:209], v201 offset:56320
	global_load_lds_dwordx4 v[180:181], off
	v_lshl_add_u64 v[180:181], v[244:245], 0, s[24:25]
	s_mov_b32 m0, s18
	s_nop 0
	global_load_lds_dwordx4 v[180:181], off
	s_barrier
	s_waitcnt lgkmcnt(0)
	s_waitcnt lgkmcnt(0)
	v_mfma_f32_16x16x32_bf16 v[62:65], v[130:133], v[146:149], v[62:65]
	v_mfma_f32_16x16x32_bf16 v[58:61], v[138:141], v[146:149], v[58:61]
	v_mfma_f32_16x16x32_bf16 v[46:49], v[130:133], v[154:157], v[46:49]
	v_mfma_f32_16x16x32_bf16 v[42:45], v[138:141], v[154:157], v[42:45]
	v_mfma_f32_16x16x32_bf16 v[30:33], v[130:133], v[170:173], v[30:33]
	v_mfma_f32_16x16x32_bf16 v[26:29], v[138:141], v[170:173], v[26:29]
	v_mfma_f32_16x16x32_bf16 v[14:17], v[130:133], v[202:205], v[14:17]
	v_mfma_f32_16x16x32_bf16 v[10:13], v[138:141], v[202:205], v[10:13]
	v_mfma_f32_16x16x32_bf16 v[62:65], v[134:137], v[150:153], v[62:65]
	v_mfma_f32_16x16x32_bf16 v[58:61], v[142:145], v[150:153], v[58:61]
	v_mfma_f32_16x16x32_bf16 v[46:49], v[134:137], v[158:161], v[46:49]
	v_mfma_f32_16x16x32_bf16 v[42:45], v[142:145], v[158:161], v[42:45]
	v_mfma_f32_16x16x32_bf16 v[30:33], v[134:137], v[174:177], v[30:33]
	v_mfma_f32_16x16x32_bf16 v[26:29], v[142:145], v[174:177], v[26:29]
	v_mfma_f32_16x16x32_bf16 v[14:17], v[134:137], v[206:209], v[14:17]
	v_mfma_f32_16x16x32_bf16 v[10:13], v[142:145], v[206:209], v[10:13]
	s_barrier
	s_add_u32 s72, s90, 0x20080
	s_addc_u32 s73, s91, 0
	s_add_i32 s6, s33, s14
	v_lshl_add_u64 v[130:131], s[72:73], 0, v[162:163]
	s_mov_b32 m0, s6
	s_nop 0
	global_load_lds_dwordx4 v[130:131], off
	v_lshl_add_u64 v[130:131], s[72:73], 0, v[164:165]
	s_add_i32 m0, s6, 0x2000
	s_nop 0
	global_load_lds_dwordx4 v[130:131], off
	s_waitcnt vmcnt(6)
	s_barrier
	v_mfma_f32_16x16x32_bf16 v[54:57], v[210:213], v[146:149], v[54:57]
	v_mfma_f32_16x16x32_bf16 v[50:53], v[218:221], v[146:149], v[50:53]
	v_mfma_f32_16x16x32_bf16 v[38:41], v[210:213], v[154:157], v[38:41]
	v_mfma_f32_16x16x32_bf16 v[34:37], v[218:221], v[154:157], v[34:37]
	v_mfma_f32_16x16x32_bf16 v[22:25], v[210:213], v[170:173], v[22:25]
	v_mfma_f32_16x16x32_bf16 v[18:21], v[218:221], v[170:173], v[18:21]
	v_mfma_f32_16x16x32_bf16 v[6:9], v[210:213], v[202:205], v[6:9]
	v_mfma_f32_16x16x32_bf16 v[2:5], v[218:221], v[202:205], v[2:5]
	v_mfma_f32_16x16x32_bf16 v[54:57], v[214:217], v[150:153], v[54:57]
	v_mfma_f32_16x16x32_bf16 v[50:53], v[222:225], v[150:153], v[50:53]
	v_mfma_f32_16x16x32_bf16 v[38:41], v[214:217], v[158:161], v[38:41]
	v_mfma_f32_16x16x32_bf16 v[34:37], v[222:225], v[158:161], v[34:37]
	v_mfma_f32_16x16x32_bf16 v[22:25], v[214:217], v[174:177], v[22:25]
	v_mfma_f32_16x16x32_bf16 v[18:21], v[222:225], v[174:177], v[18:21]
	v_mfma_f32_16x16x32_bf16 v[6:9], v[214:217], v[206:209], v[6:9]
	v_mfma_f32_16x16x32_bf16 v[2:5], v[222:225], v[206:209], v[2:5]
	s_add_i32 s69, s69, 2
	s_add_u32 s62, s62, 0x100
	s_addc_u32 s63, s63, 0
	s_add_u32 s47, s47, 0x100
	s_addc_u32 s48, s48, 0
	s_cmp_gt_u32 s69, 5
	s_barrier
	s_cbranch_scc0 .LBB0_528
	s_setprio 0
	s_lshl_b32 s21, s38, 8
	s_ashr_i32 s6, s38, 2
	s_and_b32 s21, s21, 0x300
	s_cmp_lt_u32 s38, 4
	s_cselect_b64 s[62:63], -1, 0
	s_cmp_gt_u32 s38, 3
	s_cselect_b64 s[90:91], -1, 0
	s_lshl_b32 s22, s6, 15
	s_lshl_b32 s2, s2, 8
	s_lshl_b32 s6, s6, 10
	v_or_b32_e32 v132, s21, v200
	s_sub_i32 s2, s2, s22
	s_addk_i32 s6, 0x1a00
	v_add_u32_e32 v0, s6, v132
	v_add_u32_e32 v170, s2, v179
	v_ashrrev_i32_e32 v203, 8, v0
	v_lshrrev_b32_e32 v0, 8, v170
	v_mad_i32_i24 v130, v0, 38, v203
	v_bitop3_b32 v202, s21, v243, v200 bitop3:0xc8
	v_ashrrev_i32_e32 v131, 31, v130
	v_or_b32_e32 v0, v202, v185
	v_lshlrev_b64 v[130:131], 17, v[130:131]
	v_lshl_add_u64 v[130:131], s[40:41], 0, v[130:131]
	v_lshlrev_b32_e32 v0, 1, v0
	v_lshl_add_u64 v[130:131], v[130:131], 0, v[0:1]
	global_load_dwordx4 v[154:157], v[130:131], off
	global_load_dwordx4 v[138:141], v[130:131], off offset:64
	v_lshlrev_b32_e32 v172, 1, v132
	v_mov_b32_e32 v173, v1
	v_lshl_add_u64 v[176:177], s[0:1], 0, v[172:173]
	v_mov_b32_e32 v130, 0
	s_and_b64 vcc, exec, s[62:63]
	v_ashrrev_i32_e32 v171, 31, v170
	v_mov_b32_e32 v146, 0
	v_mov_b32_e32 v147, 0
	v_mov_b32_e32 v148, 0
	v_mov_b32_e32 v149, 0
	v_mov_b32_e32 v158, 0
	v_mov_b32_e32 v159, 0
	v_mov_b32_e32 v160, 0
	v_mov_b32_e32 v161, 0
	s_cbranch_vccnz .LBB0_531
	v_lshlrev_b64 v[132:133], 11, v[170:171]
	v_lshl_add_u64 v[132:133], v[176:177], 0, v[132:133]
	global_load_dwordx4 v[158:161], v[132:133], off
	global_load_dwordx4 v[146:149], v[132:133], off offset:64

.LBB0_609:
	s_add_u32 s24, s16, 0x19c00000
	s_addc_u32 s25, s17, 0
	v_bfe_u32 v16, v8, 4, 2
	s_add_u32 s26, s16, 0x12000000
	v_and_b32_e32 v15, 15, v8
	v_lshlrev_b32_e32 v18, 4, v16
	v_lshlrev_b32_e32 v8, 2, v8
	s_addc_u32 s27, s17, 0
	s_and_b32 s3, s18, 3
	v_lshl_or_b32 v182, s19, 6, v15
	v_lshl_or_b32 v15, v15, 6, v18
	s_lshl_b32 s16, s19, 13
	v_and_b32_e32 v8, 32, v8
	s_mov_b64 s[28:29], 0x80
	v_bitop3_b32 v18, v15, s16, v8 bitop3:0xde
	s_lshl_b32 s16, s3, 12
	s_add_i32 m0, s11, 0x18000
	v_lshl_add_u64 v[6:7], v[6:7], 0, s[28:29]
	v_bitop3_b32 v183, v15, s16, v8 bitop3:0xde
	s_waitcnt vmcnt(4)
	s_barrier
	global_load_lds_dwordx4 v[6:7], off
	v_lshl_add_u64 v[4:5], v[4:5], 0, s[28:29]
	s_add_i32 m0, s11, 0x1a000
	s_add_i32 s16, s11, 0x8000
	s_add_i32 s17, s11, 0xa000
	global_load_lds_dwordx4 v[4:5], off
	v_lshl_add_u64 v[2:3], v[2:3], 0, s[28:29]
	s_mov_b32 m0, s16
	s_add_u32 s18, s52, 0x40080
	global_load_lds_dwordx4 v[2:3], off
	v_lshl_add_u64 v[0:1], v[0:1], 0, s[28:29]
	s_mov_b32 m0, s17
	s_addc_u32 s19, s53, 0
	global_load_lds_dwordx4 v[0:1], off
	s_add_i32 m0, s11, 0x1c000
	v_lshl_add_u64 v[0:1], s[18:19], 0, v[160:161]
	global_load_lds_dwordx4 v[0:1], off
	v_lshl_add_u64 v[0:1], s[18:19], 0, v[162:163]
	s_add_i32 m0, s11, 0x1e000
	v_lshlrev_b32_e32 v17, 3, v16
	global_load_lds_dwordx4 v[0:1], off
	v_lshlrev_b32_e32 v0, 14, v9
	v_and_b32_e32 v0, 0xffff8000, v0
	v_lshl_add_u32 v0, v10, 11, v0
	v_and_b32_e32 v1, 1, v9
	v_lshl_or_b32 v0, v1, 6, v0
	v_lshl_add_u32 v164, v11, 1, v0
	v_lshlrev_b32_e32 v0, 14, v12
	v_and_b32_e32 v0, 0xffff8000, v0
	s_waitcnt vmcnt(6)
	v_lshl_add_u32 v0, v13, 11, v0
	v_and_b32_e32 v1, 1, v12
	v_lshl_or_b32 v0, v1, 6, v0
	s_add_i32 s19, 0, 0x10000
	s_add_i32 s20, 0, 0x14000
	v_lshl_or_b32 v184, s3, 6, v17
	v_cmp_eq_u32_e64 s[36:37], 0, v16
	s_ashr_i32 s18, s4, 31
	v_mov_b32_e32 v165, v161
	v_lshl_add_u32 v166, v14, 1, v0
	v_mov_b32_e32 v167, v161
	v_mov_b64_e32 v[168:169], 0x400
	v_mov_b64_e32 v[170:171], 0x3ff
	v_add_u32_e32 v185, s19, v183
	v_add_u32_e32 v186, 0, v18
	v_add_u32_e32 v187, s20, v183
	s_barrier
	s_branch .LBB0_611
	s_nop 0
	s_nop 0
	s_nop 0
	s_nop 0
	s_nop 0
	s_nop 0
	s_nop 0
	s_nop 0
	s_nop 0
	s_nop 0
	s_nop 0

.LBB0_618:
	s_cmp_ge_u32 s11, 0x1000
	s_cbranch_scc0 .Lsp_3
	s_setprio 1
.Lsp_3:
	ds_read_b128 v[48:51], v185
	ds_read_b128 v[52:55], v185 offset:1024
	ds_read_b128 v[56:59], v185 offset:2048
	ds_read_b128 v[60:63], v185 offset:3072
	s_add_u32 s47, s48, 0xfffc0080
	s_addc_u32 s50, s49, -1
	s_cmp_eq_u32 s35, 12
	s_cselect_b32 s55, s3, s50
	s_cselect_b32 s54, s21, s47
	s_cselect_b32 s53, s22, s33
	s_cselect_b32 s52, s23, s31
	v_lshl_add_u64 v[180:181], s[48:49], 0, v[164:165]
	s_add_i32 m0, s11, 0xc000
	ds_read_b128 v[144:147], v186
	ds_read_b128 v[148:151], v186 offset:1024
	ds_read_b128 v[152:155], v186 offset:2048
	ds_read_b128 v[156:159], v186 offset:3072
	ds_read_b128 v[172:175], v186 offset:4096
	ds_read_b128 v[176:179], v186 offset:5120
	ds_read_b128 v[188:191], v186 offset:6144
	ds_read_b128 v[192:195], v186 offset:7168
	global_load_lds_dwordx4 v[180:181], off
	v_lshl_add_u64 v[180:181], s[48:49], 0, v[166:167]
	s_add_i32 m0, s11, 0xe000
	s_nop 0
	global_load_lds_dwordx4 v[180:181], off
	s_waitcnt lgkmcnt(8)
	s_barrier
	s_waitcnt lgkmcnt(0)
	s_waitcnt lgkmcnt(0)
	v_mfma_f32_16x16x32_bf16 v[140:143], v[48:51], v[144:147], v[140:143]
	v_mfma_f32_16x16x32_bf16 v[136:139], v[56:59], v[144:147], v[136:139]
	v_mfma_f32_16x16x32_bf16 v[124:127], v[48:51], v[152:155], v[124:127]
	v_mfma_f32_16x16x32_bf16 v[120:123], v[56:59], v[152:155], v[120:123]
	v_mfma_f32_16x16x32_bf16 v[108:111], v[48:51], v[172:175], v[108:111]
	v_mfma_f32_16x16x32_bf16 v[104:107], v[56:59], v[172:175], v[104:107]
	v_mfma_f32_16x16x32_bf16 v[92:95], v[48:51], v[188:191], v[92:95]
	v_mfma_f32_16x16x32_bf16 v[88:91], v[56:59], v[188:191], v[88:91]
	v_mfma_f32_16x16x32_bf16 v[140:143], v[52:55], v[148:151], v[140:143]
	v_mfma_f32_16x16x32_bf16 v[136:139], v[60:63], v[148:151], v[136:139]
	v_mfma_f32_16x16x32_bf16 v[124:127], v[52:55], v[156:159], v[124:127]
	v_mfma_f32_16x16x32_bf16 v[120:123], v[60:63], v[156:159], v[120:123]
	v_mfma_f32_16x16x32_bf16 v[108:111], v[52:55], v[176:179], v[108:111]
	v_mfma_f32_16x16x32_bf16 v[104:107], v[60:63], v[176:179], v[104:107]
	v_mfma_f32_16x16x32_bf16 v[92:95], v[52:55], v[192:195], v[92:95]
	v_mfma_f32_16x16x32_bf16 v[88:91], v[60:63], v[192:195], v[88:91]
	s_barrier
	s_add_i32 s47, s19, s10
	v_lshl_add_u64 v[180:181], s[52:53], 0, v[160:161]
	s_mov_b32 m0, s47
	ds_read_b128 v[196:199], v187
	ds_read_b128 v[200:203], v187 offset:1024
	ds_read_b128 v[204:207], v187 offset:2048
	ds_read_b128 v[208:211], v187 offset:3072
	global_load_lds_dwordx4 v[180:181], off
	v_lshl_add_u64 v[212:213], s[52:53], 0, v[162:163]
	s_add_i32 m0, s47, 0x2000
	s_nop 0
	global_load_lds_dwordx4 v[212:213], off
	s_barrier
	s_waitcnt lgkmcnt(0)
	s_waitcnt lgkmcnt(0)
	v_mfma_f32_16x16x32_bf16 v[132:135], v[196:199], v[144:147], v[132:135]
	v_mfma_f32_16x16x32_bf16 v[128:131], v[204:207], v[144:147], v[128:131]
	v_mfma_f32_16x16x32_bf16 v[116:119], v[196:199], v[152:155], v[116:119]
	v_mfma_f32_16x16x32_bf16 v[112:115], v[204:207], v[152:155], v[112:115]
	v_mfma_f32_16x16x32_bf16 v[100:103], v[196:199], v[172:175], v[100:103]
	v_mfma_f32_16x16x32_bf16 v[96:99], v[204:207], v[172:175], v[96:99]
	v_mfma_f32_16x16x32_bf16 v[84:87], v[196:199], v[188:191], v[84:87]
	v_mfma_f32_16x16x32_bf16 v[80:83], v[204:207], v[188:191], v[80:83]
	v_mfma_f32_16x16x32_bf16 v[132:135], v[200:203], v[148:151], v[132:135]
	v_mfma_f32_16x16x32_bf16 v[128:131], v[208:211], v[148:151], v[128:131]
	v_mfma_f32_16x16x32_bf16 v[116:119], v[200:203], v[156:159], v[116:119]
	v_mfma_f32_16x16x32_bf16 v[112:115], v[208:211], v[156:159], v[112:115]
	v_mfma_f32_16x16x32_bf16 v[100:103], v[200:203], v[176:179], v[100:103]
	v_mfma_f32_16x16x32_bf16 v[96:99], v[208:211], v[176:179], v[96:99]
	v_mfma_f32_16x16x32_bf16 v[84:87], v[200:203], v[192:195], v[84:87]
	v_mfma_f32_16x16x32_bf16 v[80:83], v[208:211], v[192:195], v[80:83]
	s_mov_b32 m0, s11
	v_lshl_add_u64 v[214:215], s[54:55], 0, v[160:161]
	s_barrier
	ds_read_b128 v[144:147], v186 offset:16384
	ds_read_b128 v[148:151], v186 offset:17408
	ds_read_b128 v[152:155], v186 offset:18432
	ds_read_b128 v[156:159], v186 offset:19456
	ds_read_b128 v[172:175], v186 offset:20480
	ds_read_b128 v[176:179], v186 offset:21504
	ds_read_b128 v[188:191], v186 offset:22528
	ds_read_b128 v[192:195], v186 offset:23552
	global_load_lds_dwordx4 v[214:215], off
	v_lshl_add_u64 v[216:217], s[54:55], 0, v[162:163]
	s_mov_b32 m0, s12
	s_nop 0
	global_load_lds_dwordx4 v[216:217], off
	s_barrier
	s_waitcnt lgkmcnt(0)
	s_waitcnt lgkmcnt(0)
	v_mfma_f32_16x16x32_bf16 v[76:79], v[48:51], v[144:147], v[76:79]
	v_mfma_f32_16x16x32_bf16 v[72:75], v[56:59], v[144:147], v[72:75]
	v_mfma_f32_16x16x32_bf16 v[44:47], v[48:51], v[152:155], v[44:47]
	v_mfma_f32_16x16x32_bf16 v[40:43], v[56:59], v[152:155], v[40:43]
	v_mfma_f32_16x16x32_bf16 v[28:31], v[48:51], v[172:175], v[28:31]
	v_mfma_f32_16x16x32_bf16 v[24:27], v[56:59], v[172:175], v[24:27]
	v_mfma_f32_16x16x32_bf16 v[12:15], v[48:51], v[188:191], v[12:15]
	v_mfma_f32_16x16x32_bf16 v[8:11], v[56:59], v[188:191], v[8:11]
	v_mfma_f32_16x16x32_bf16 v[76:79], v[52:55], v[148:151], v[76:79]
	v_mfma_f32_16x16x32_bf16 v[72:75], v[60:63], v[148:151], v[72:75]
	v_mfma_f32_16x16x32_bf16 v[44:47], v[52:55], v[156:159], v[44:47]
	v_mfma_f32_16x16x32_bf16 v[40:43], v[60:63], v[156:159], v[40:43]
	v_mfma_f32_16x16x32_bf16 v[28:31], v[52:55], v[176:179], v[28:31]
	v_mfma_f32_16x16x32_bf16 v[24:27], v[60:63], v[176:179], v[24:27]
	v_mfma_f32_16x16x32_bf16 v[12:15], v[52:55], v[192:195], v[12:15]
	v_mfma_f32_16x16x32_bf16 v[8:11], v[60:63], v[192:195], v[8:11]
	s_barrier
	s_add_u32 s50, s52, 0x40000
	s_addc_u32 s51, s53, 0
	s_add_i32 s47, s20, s10
	v_lshl_add_u64 v[48:49], s[50:51], 0, v[160:161]
	s_mov_b32 m0, s47
	s_nop 0
	global_load_lds_dwordx4 v[48:49], off
	v_lshl_add_u64 v[48:49], s[50:51], 0, v[162:163]
	s_add_i32 m0, s47, 0x2000
	s_nop 0
	global_load_lds_dwordx4 v[48:49], off
	s_waitcnt vmcnt(6)
	s_barrier
	v_mfma_f32_16x16x32_bf16 v[36:39], v[196:199], v[152:155], v[36:39]
	v_mfma_f32_16x16x32_bf16 v[32:35], v[204:207], v[152:155], v[32:35]
	v_mfma_f32_16x16x32_bf16 v[20:23], v[196:199], v[172:175], v[20:23]
	v_mfma_f32_16x16x32_bf16 v[16:19], v[204:207], v[172:175], v[16:19]
	v_mfma_f32_16x16x32_bf16 v[4:7], v[196:199], v[188:191], v[4:7]
	v_mfma_f32_16x16x32_bf16 v[0:3], v[204:207], v[188:191], v[0:3]
	v_mfma_f32_16x16x32_bf16 v[48:51], v[196:199], v[144:147], v[68:71]
	v_mfma_f32_16x16x32_bf16 v[52:55], v[204:207], v[144:147], v[64:67]
	v_mfma_f32_16x16x32_bf16 v[36:39], v[200:203], v[156:159], v[36:39]
	v_mfma_f32_16x16x32_bf16 v[32:35], v[208:211], v[156:159], v[32:35]
	v_mfma_f32_16x16x32_bf16 v[20:23], v[200:203], v[176:179], v[20:23]
	v_mfma_f32_16x16x32_bf16 v[16:19], v[208:211], v[176:179], v[16:19]
	v_mfma_f32_16x16x32_bf16 v[4:7], v[200:203], v[192:195], v[4:7]
	v_mfma_f32_16x16x32_bf16 v[0:3], v[208:211], v[192:195], v[0:3]
	v_mfma_f32_16x16x32_bf16 v[48:51], v[200:203], v[148:151], v[48:51]
	v_mfma_f32_16x16x32_bf16 v[52:55], v[208:211], v[148:151], v[52:55]
	s_add_i32 s47, 0, 0x18000
	v_add_u32_e32 v68, s47, v183
	s_barrier
	ds_read_b128 v[56:59], v68
	ds_read_b128 v[60:63], v68 offset:1024
	ds_read_b128 v[64:67], v68 offset:2048
	ds_read_b128 v[68:71], v68 offset:3072
	s_add_u32 s50, s54, 0x40000
	s_addc_u32 s51, s55, 0
	s_mov_b32 m0, s13
	v_lshl_add_u64 v[196:197], s[50:51], 0, v[160:161]
	ds_read_b128 v[144:147], v186 offset:32768
	ds_read_b128 v[148:151], v186 offset:33792
	ds_read_b128 v[152:155], v186 offset:34816
	ds_read_b128 v[156:159], v186 offset:35840
	ds_read_b128 v[172:175], v186 offset:36864
	ds_read_b128 v[176:179], v186 offset:37888
	ds_read_b128 v[188:191], v186 offset:38912
	ds_read_b128 v[192:195], v186 offset:39936
	global_load_lds_dwordx4 v[196:197], off
	v_lshl_add_u64 v[196:197], s[50:51], 0, v[162:163]
	s_mov_b32 m0, s14
	s_nop 0
	global_load_lds_dwordx4 v[196:197], off
	s_waitcnt lgkmcnt(8)
	s_barrier
	s_waitcnt lgkmcnt(0)
	s_waitcnt lgkmcnt(0)
	v_mfma_f32_16x16x32_bf16 v[140:143], v[56:59], v[144:147], v[140:143]
	v_mfma_f32_16x16x32_bf16 v[136:139], v[64:67], v[144:147], v[136:139]
	v_mfma_f32_16x16x32_bf16 v[124:127], v[56:59], v[152:155], v[124:127]
	v_mfma_f32_16x16x32_bf16 v[120:123], v[64:67], v[152:155], v[120:123]
	v_mfma_f32_16x16x32_bf16 v[108:111], v[56:59], v[172:175], v[108:111]
	v_mfma_f32_16x16x32_bf16 v[104:107], v[64:67], v[172:175], v[104:107]
	v_mfma_f32_16x16x32_bf16 v[92:95], v[56:59], v[188:191], v[92:95]
	v_mfma_f32_16x16x32_bf16 v[88:91], v[64:67], v[188:191], v[88:91]
	v_mfma_f32_16x16x32_bf16 v[140:143], v[60:63], v[148:151], v[140:143]
	v_mfma_f32_16x16x32_bf16 v[136:139], v[68:71], v[148:151], v[136:139]
	v_mfma_f32_16x16x32_bf16 v[124:127], v[60:63], v[156:159], v[124:127]
	v_mfma_f32_16x16x32_bf16 v[120:123], v[68:71], v[156:159], v[120:123]
	v_mfma_f32_16x16x32_bf16 v[108:111], v[60:63], v[176:179], v[108:111]
	v_mfma_f32_16x16x32_bf16 v[104:107], v[68:71], v[176:179], v[104:107]
	v_mfma_f32_16x16x32_bf16 v[92:95], v[60:63], v[192:195], v[92:95]
	v_mfma_f32_16x16x32_bf16 v[88:91], v[68:71], v[192:195], v[88:91]
	s_barrier
	s_add_i32 s54, 0, 0x1c000
	s_add_i32 s47, s47, s10
	v_add_u32_e32 v208, s54, v183
	v_lshl_add_u64 v[180:181], v[180:181], 0, s[28:29]
	s_mov_b32 m0, s47
	ds_read_b128 v[196:199], v208
	ds_read_b128 v[200:203], v208 offset:1024
	ds_read_b128 v[204:207], v208 offset:2048
	ds_read_b128 v[208:211], v208 offset:3072
	global_load_lds_dwordx4 v[180:181], off
	v_lshl_add_u64 v[180:181], v[212:213], 0, s[28:29]
	s_add_i32 m0, s47, 0x2000
	s_nop 0
	global_load_lds_dwordx4 v[180:181], off
	s_barrier
	s_waitcnt lgkmcnt(0)
	s_waitcnt lgkmcnt(0)
	v_mfma_f32_16x16x32_bf16 v[132:135], v[196:199], v[144:147], v[132:135]
	v_mfma_f32_16x16x32_bf16 v[128:131], v[204:207], v[144:147], v[128:131]
	v_mfma_f32_16x16x32_bf16 v[116:119], v[196:199], v[152:155], v[116:119]
	v_mfma_f32_16x16x32_bf16 v[112:115], v[204:207], v[152:155], v[112:115]
	v_mfma_f32_16x16x32_bf16 v[100:103], v[196:199], v[172:175], v[100:103]
	v_mfma_f32_16x16x32_bf16 v[96:99], v[204:207], v[172:175], v[96:99]
	v_mfma_f32_16x16x32_bf16 v[84:87], v[196:199], v[188:191], v[84:87]
	v_mfma_f32_16x16x32_bf16 v[80:83], v[204:207], v[188:191], v[80:83]
	v_mfma_f32_16x16x32_bf16 v[132:135], v[200:203], v[148:151], v[132:135]
	v_mfma_f32_16x16x32_bf16 v[128:131], v[208:211], v[148:151], v[128:131]
	v_mfma_f32_16x16x32_bf16 v[116:119], v[200:203], v[156:159], v[116:119]
	v_mfma_f32_16x16x32_bf16 v[112:115], v[208:211], v[156:159], v[112:115]
	v_mfma_f32_16x16x32_bf16 v[100:103], v[200:203], v[176:179], v[100:103]
	v_mfma_f32_16x16x32_bf16 v[96:99], v[208:211], v[176:179], v[96:99]
	v_mfma_f32_16x16x32_bf16 v[84:87], v[200:203], v[192:195], v[84:87]
	v_mfma_f32_16x16x32_bf16 v[80:83], v[208:211], v[192:195], v[80:83]
	s_mov_b32 m0, s16
	v_lshl_add_u64 v[180:181], v[214:215], 0, s[28:29]
	s_barrier
	ds_read_b128 v[144:147], v186 offset:49152
	ds_read_b128 v[148:151], v186 offset:50176
	ds_read_b128 v[152:155], v186 offset:51200
	ds_read_b128 v[156:159], v186 offset:52224
	ds_read_b128 v[172:175], v186 offset:53248
	ds_read_b128 v[176:179], v186 offset:54272
	ds_read_b128 v[188:191], v186 offset:55296
	ds_read_b128 v[192:195], v186 offset:56320
	global_load_lds_dwordx4 v[180:181], off
	v_lshl_add_u64 v[180:181], v[216:217], 0, s[28:29]
	s_mov_b32 m0, s17
	s_nop 0
	global_load_lds_dwordx4 v[180:181], off
	s_barrier
	s_waitcnt lgkmcnt(0)
	s_waitcnt lgkmcnt(0)
	v_mfma_f32_16x16x32_bf16 v[76:79], v[56:59], v[144:147], v[76:79]
	v_mfma_f32_16x16x32_bf16 v[72:75], v[64:67], v[144:147], v[72:75]
	v_mfma_f32_16x16x32_bf16 v[44:47], v[56:59], v[152:155], v[44:47]
	v_mfma_f32_16x16x32_bf16 v[40:43], v[64:67], v[152:155], v[40:43]
	v_mfma_f32_16x16x32_bf16 v[28:31], v[56:59], v[172:175], v[28:31]
	v_mfma_f32_16x16x32_bf16 v[24:27], v[64:67], v[172:175], v[24:27]
	v_mfma_f32_16x16x32_bf16 v[12:15], v[56:59], v[188:191], v[12:15]
	v_mfma_f32_16x16x32_bf16 v[8:11], v[64:67], v[188:191], v[8:11]
	v_mfma_f32_16x16x32_bf16 v[76:79], v[60:63], v[148:151], v[76:79]
	v_mfma_f32_16x16x32_bf16 v[72:75], v[68:71], v[148:151], v[72:75]
	v_mfma_f32_16x16x32_bf16 v[44:47], v[60:63], v[156:159], v[44:47]
	v_mfma_f32_16x16x32_bf16 v[40:43], v[68:71], v[156:159], v[40:43]
	v_mfma_f32_16x16x32_bf16 v[28:31], v[60:63], v[176:179], v[28:31]
	v_mfma_f32_16x16x32_bf16 v[24:27], v[68:71], v[176:179], v[24:27]
	v_mfma_f32_16x16x32_bf16 v[12:15], v[60:63], v[192:195], v[12:15]
	v_mfma_f32_16x16x32_bf16 v[8:11], v[68:71], v[192:195], v[8:11]
	s_barrier
	s_add_u32 s50, s52, 0x40080
	s_addc_u32 s51, s53, 0
	s_add_i32 s47, s54, s10
	v_lshl_add_u64 v[56:57], s[50:51], 0, v[160:161]
	s_mov_b32 m0, s47
	s_nop 0
	global_load_lds_dwordx4 v[56:57], off
	v_lshl_add_u64 v[56:57], s[50:51], 0, v[162:163]
	s_add_i32 m0, s47, 0x2000
	s_nop 0
	global_load_lds_dwordx4 v[56:57], off
	s_waitcnt vmcnt(6)
	s_barrier
	v_mfma_f32_16x16x32_bf16 v[48:51], v[196:199], v[144:147], v[48:51]
	v_mfma_f32_16x16x32_bf16 v[68:71], v[200:203], v[148:151], v[48:51]
	v_mfma_f32_16x16x32_bf16 v[48:51], v[204:207], v[144:147], v[52:55]
	v_mfma_f32_16x16x32_bf16 v[36:39], v[196:199], v[152:155], v[36:39]
	v_mfma_f32_16x16x32_bf16 v[32:35], v[204:207], v[152:155], v[32:35]
	v_mfma_f32_16x16x32_bf16 v[20:23], v[196:199], v[172:175], v[20:23]
	v_mfma_f32_16x16x32_bf16 v[16:19], v[204:207], v[172:175], v[16:19]
	v_mfma_f32_16x16x32_bf16 v[4:7], v[196:199], v[188:191], v[4:7]
	v_mfma_f32_16x16x32_bf16 v[0:3], v[204:207], v[188:191], v[0:3]
	v_mfma_f32_16x16x32_bf16 v[64:67], v[208:211], v[148:151], v[48:51]
	v_mfma_f32_16x16x32_bf16 v[36:39], v[200:203], v[156:159], v[36:39]
	v_mfma_f32_16x16x32_bf16 v[32:35], v[208:211], v[156:159], v[32:35]
	v_mfma_f32_16x16x32_bf16 v[20:23], v[200:203], v[176:179], v[20:23]
	v_mfma_f32_16x16x32_bf16 v[16:19], v[208:211], v[176:179], v[16:19]
	v_mfma_f32_16x16x32_bf16 v[4:7], v[200:203], v[192:195], v[4:7]
	v_mfma_f32_16x16x32_bf16 v[0:3], v[208:211], v[192:195], v[0:3]
	s_add_i32 s35, s35, 2
	s_add_u32 s48, s48, 0x100
	s_addc_u32 s49, s49, 0
	s_add_u32 s31, s31, 0x100
	s_addc_u32 s33, s33, 0
	s_cmp_gt_u32 s35, 13
	s_barrier
	s_cbranch_scc0 .LBB0_618
	s_setprio 0
	v_and_b32_e32 v145, 64, v229
	v_xor_b32_e32 v144, 16, v229
	v_add_u32_e32 v145, 64, v145
	v_cmp_lt_i32_e32 vcc, v144, v145
	v_lshl_or_b32 v172, s46, 8, v184
	v_ashrrev_i32_e32 v173, 31, v172
	v_cndmask_b32_e32 v144, v229, v144, vcc
	v_lshl_add_u32 v174, s2, 8, v182
	v_lshlrev_b32_e32 v189, 2, v144
	v_xor_b32_e32 v144, 32, v229
	v_lshlrev_b64 v[206:207], 2, v[172:173]
	v_cmp_lt_i32_e32 vcc, v144, v145
	v_ashrrev_i32_e32 v175, 31, v174
	v_lshl_add_u64 v[176:177], s[44:45], 0, v[206:207]
	v_cndmask_b32_e32 v144, v229, v144, vcc
	v_lshlrev_b64 v[208:209], 12, v[174:175]
	v_lshl_add_u64 v[56:57], s[56:57], 0, v[206:207]
	v_lshlrev_b32_e32 v188, 2, v144
	v_lshl_add_u64 v[144:145], v[176:177], 0, v[208:209]
	global_load_dwordx4 v[52:55], v[56:57], off offset:16
	global_load_dwordx4 v[60:63], v[56:57], off
	global_load_dwordx4 v[48:51], v[56:57], off offset:144
	s_nop 0
	global_load_dwordx4 v[56:59], v[56:57], off offset:128
	s_nop 0
	global_load_dwordx4 v[190:193], v[144:145], off offset:16
	global_load_dwordx4 v[194:197], v[144:145], off
	global_load_dwordx4 v[198:201], v[144:145], off offset:144
	global_load_dwordx4 v[202:205], v[144:145], off offset:128
	v_or_b32_e32 v178, 16, v174
	v_ashrrev_i32_e32 v179, 31, v178
	v_lshlrev_b64 v[180:181], 12, v[178:179]
	v_lshl_add_u64 v[148:149], v[176:177], 0, v[180:181]
	global_load_dwordx4 v[152:155], v[148:149], off offset:16
	global_load_dwordx4 v[156:159], v[148:149], off
	global_load_dwordx4 v[144:147], v[148:149], off offset:144
	s_nop 0
	global_load_dwordx4 v[148:151], v[148:149], off offset:128
	s_waitcnt vmcnt(0)
	v_pk_add_f32 v[136:137], v[136:137], v[190:191]
	v_pk_add_f32 v[194:195], v[140:141], v[194:195]
	v_pk_add_f32 v[198:199], v[128:129], v[198:199]
	v_lshl_add_u64 v[128:129], s[78:79], 0, v[208:209]
	v_pk_add_f32 v[196:197], v[142:143], v[196:197]
	v_pk_mul_f32 v[212:213], v[194:195], v[194:195]
	v_pk_add_f32 v[190:191], v[132:133], v[202:203]
	v_lshl_add_u64 v[128:129], v[128:129], 0, v[206:207]
	v_pk_mul_f32 v[210:211], v[196:197], v[196:197]
	v_pk_add_f32 v[138:139], v[138:139], v[192:193]
	v_pk_add_f32 v[192:193], v[134:135], v[204:205]
	v_pk_mul_f32 v[204:205], v[190:191], v[190:191]
	v_pk_add_f32 v[200:201], v[130:131], v[200:201]
	global_store_dwordx4 v[128:129], v[194:197], off nt
	global_store_dwordx4 v[128:129], v[136:139], off offset:16 nt
	global_store_dwordx4 v[128:129], v[190:193], off offset:128 nt
	global_store_dwordx4 v[128:129], v[198:201], off offset:144 nt
	v_pk_mul_f32 v[134:135], v[56:57], v[190:191]
	v_add_f32_e32 v190, v212, v213
	v_add_f32_e32 v190, v210, v190
	v_pk_mul_f32 v[216:217], v[136:137], v[136:137]
	v_add_f32_e32 v190, v211, v190
	v_add_f32_e32 v190, v216, v190
	v_pk_mul_f32 v[214:215], v[138:139], v[138:139]
	v_add_f32_e32 v190, v217, v190
	v_add_f32_e32 v190, v214, v190
	v_add_f32_e32 v190, v215, v190
	v_add_f32_e32 v190, v204, v190
	v_pk_mul_f32 v[202:203], v[192:193], v[192:193]
	v_add_f32_e32 v190, v205, v190
	v_add_f32_e32 v190, v202, v190
	v_pk_mul_f32 v[220:221], v[198:199], v[198:199]
	v_add_f32_e32 v190, v203, v190
	v_add_f32_e32 v190, v220, v190
	v_pk_mul_f32 v[218:219], v[200:201], v[200:201]
	v_add_f32_e32 v190, v221, v190
	v_add_f32_e32 v190, v218, v190
	v_pk_mul_f32 v[128:129], v[62:63], v[196:197]
	v_add_f32_e32 v196, v219, v190
	v_lshlrev_b64 v[190:191], 11, v[174:175]
	v_pk_mul_f32 v[142:143], v[60:61], v[194:195]
	v_pk_mul_f32 v[130:131], v[52:53], v[136:137]
	v_pk_mul_f32 v[132:133], v[54:55], v[138:139]
	v_lshl_add_u64 v[190:191], s[24:25], 0, v[190:191]
	v_pk_mul_f32 v[136:137], v[58:59], v[192:193]
	v_pk_mul_f32 v[138:139], v[48:49], v[198:199]
	v_pk_mul_f32 v[140:141], v[50:51], v[200:201]
	v_lshl_add_u64 v[194:195], v[172:173], 1, v[190:191]
	v_cvt_pk_bf16_f32 v190, v142, v143
	v_cvt_pk_bf16_f32 v191, v128, v129
	v_cvt_pk_bf16_f32 v192, v130, v131
	v_cvt_pk_bf16_f32 v193, v132, v133
	v_cvt_pk_bf16_f32 v128, v134, v135
	v_cvt_pk_bf16_f32 v129, v136, v137
	v_cvt_pk_bf16_f32 v130, v138, v139
	v_cvt_pk_bf16_f32 v131, v140, v141
	global_store_dwordx4 v[194:195], v[190:193], off nt
	global_store_dwordx4 v[194:195], v[128:131], off offset:64 nt
	ds_bpermute_b32 v128, v189, v196
	s_waitcnt lgkmcnt(0)
	v_add_f32_e32 v128, v196, v128
	ds_bpermute_b32 v129, v188, v128
	s_and_saveexec_b64 s[2:3], s[36:37]
	s_cbranch_execz .LBB0_621
	v_lshl_add_u64 v[130:131], v[174:175], 2, s[26:27]
	s_waitcnt lgkmcnt(0)
	v_add_f32_e32 v128, v128, v129
	global_atomic_add_f32 v[130:131], v128, off

.LBB0_698:
	v_readlane_b32 s20, v254, 1
	v_readlane_b32 s21, v254, 2
	v_readlane_b32 s22, v254, 3
	v_readlane_b32 s23, v254, 4
	v_readlane_b32 s24, v254, 5
	v_readlane_b32 s25, v254, 6
	v_readlane_b32 s26, v254, 7
	v_readlane_b32 s27, v254, 8
	s_mov_b64 s[20:21], s[24:25]
	s_add_u32 s96, s20, 0x2c00
	s_addc_u32 s97, s21, 0
	s_add_u32 s86, s20, 0x5800
	s_addc_u32 s87, s21, 0
	s_add_u32 s28, s2, 0x21c00000
	s_addc_u32 s29, s3, 0
	s_add_u32 s30, s2, 0x14000000
	v_lshrrev_b32_e32 v16, 1, v8
	s_addc_u32 s31, s3, 0
	v_and_b32_e32 v16, 24, v16
	s_add_u32 s34, s2, 0x12000000
	v_and_b32_e32 v15, 15, v8
	v_lshlrev_b32_e32 v17, 1, v16
	v_lshlrev_b32_e32 v18, 2, v8
	s_addc_u32 s35, s3, 0
	v_lshl_or_b32 v17, v15, 6, v17
	s_lshl_b32 s2, s10, 13
	v_and_b32_e32 v18, 32, v18
	v_bitop3_b32 v19, v17, s2, v18 bitop3:0xde
	s_lshl_b32 s2, s17, 5
	s_mov_b64 s[52:53], 0x80
	s_and_b32 s20, s2, 0x60
	s_add_i32 m0, s12, 0x18000
	v_lshl_add_u64 v[6:7], v[6:7], 0, s[52:53]
	s_lshl_b32 s2, s20, 7
	s_waitcnt vmcnt(4)
	s_barrier
	global_load_lds_dwordx4 v[6:7], off
	v_lshl_add_u64 v[4:5], v[4:5], 0, s[52:53]
	s_add_i32 m0, s12, 0x1a000
	s_add_i32 s17, s12, 0x8000
	s_add_i32 s18, s12, 0xa000
	v_bitop3_b32 v232, v17, s2, v18 bitop3:0xde
	global_load_lds_dwordx4 v[4:5], off
	v_lshl_add_u64 v[2:3], v[2:3], 0, s[52:53]
	s_mov_b32 m0, s17
	s_add_u32 s2, s0, 0x40080
	global_load_lds_dwordx4 v[2:3], off
	v_lshl_add_u64 v[0:1], v[0:1], 0, s[52:53]
	s_mov_b32 m0, s18
	s_addc_u32 s3, s1, 0
	global_load_lds_dwordx4 v[0:1], off
	s_add_i32 m0, s12, 0x1c000
	v_lshl_add_u64 v[0:1], s[2:3], 0, v[160:161]
	global_load_lds_dwordx4 v[0:1], off
	v_lshl_add_u64 v[0:1], s[2:3], 0, v[162:163]
	s_add_i32 m0, s12, 0x1e000
	v_cmp_eq_u32_e64 s[38:39], 15, v15
	global_load_lds_dwordx4 v[0:1], off
	s_nop 0
	v_cndmask_b32_e64 v0, -1, 3, s[38:39]
	v_cmp_ne_u32_e32 vcc, 14, v15
	v_cmp_eq_u32_e64 s[42:43], 0, v15
	v_and_b32_e32 v1, 1, v9
	v_cndmask_b32_e32 v233, 2, v0, vcc
	v_cmp_eq_u32_e32 vcc, 1, v15
	s_waitcnt vmcnt(6)
	v_or_b32_e32 v235, s20, v16
	s_add_i32 s20, 0, 0x10000
	v_cndmask_b32_e64 v0, -1, 1, vcc
	v_cndmask_b32_e64 v234, v0, 0, s[42:43]
	v_and_b32_e32 v0, 14, v8
	v_cmp_eq_u32_e64 s[74:75], 14, v0
	v_lshlrev_b32_e32 v0, 14, v9
	v_and_b32_e32 v0, 0xffff8000, v0
	v_lshl_add_u32 v0, v10, 11, v0
	v_lshl_or_b32 v0, v1, 6, v0
	v_lshl_add_u32 v166, v11, 1, v0
	v_lshlrev_b32_e32 v0, 14, v12
	v_and_b32_e32 v0, 0xffff8000, v0
	v_lshl_add_u32 v0, v13, 11, v0
	v_and_b32_e32 v1, 1, v12
	v_lshl_or_b32 v0, v1, 6, v0
	s_add_i32 s21, 0, 0x14000
	v_lshl_or_b32 v231, s10, 6, v15
	v_cmp_ne_u32_e64 s[36:37], 15, v15
	v_cmp_ne_u32_e64 s[40:41], 0, v15
	v_cmp_gt_u32_e64 s[70:71], 2, v15
	s_ashr_i32 s19, s4, 31
	v_mov_b32_e32 v167, v165
	v_lshl_add_u32 v168, v14, 1, v0
	v_mov_b32_e32 v169, v165
	v_mov_b64_e32 v[170:171], 0x1600
	v_mov_b64_e32 v[172:173], 0x15ff
	v_add_u32_e32 v236, s20, v232
	v_add_u32_e32 v237, 0, v19
	v_add_u32_e32 v238, s21, v232
	v_mov_b32_e32 v239, 0x358637bd
	s_mov_b32 s33, 0x800000
	s_movk_i32 s65, 0xb00
	s_mov_b32 s54, 0xbf38aa3b
	s_mov_b32 s56, 0x3e6d3388
	s_mov_b32 s58, 0x3f07dc22
	s_mov_b32 s64, 0xbf3a00e3
	s_mov_b32 s66, 0x3f35f0e3
	s_mov_b32 s68, 0xbe11a98e
	s_mov_b32 s72, 0x3e027906
	s_mov_b64 s[22:23], s[26:27]
	s_barrier
	s_branch .LBB0_700
	s_nop 0
	s_nop 0
	s_nop 0
	s_nop 0
	s_nop 0
	s_nop 0
	s_nop 0
	s_nop 0
	s_nop 0
	s_nop 0
	s_nop 0

.LBB0_703:
	s_cmp_ge_u32 s12, 0x1000
	s_cbranch_scc0 .Lsp_4
	s_setprio 1
.Lsp_4:
	ds_read_b128 v[44:47], v236
	ds_read_b128 v[48:51], v236 offset:1024
	ds_read_b128 v[52:55], v236 offset:2048
	ds_read_b128 v[56:59], v236 offset:3072
	s_add_u32 s0, vcc_lo, 0xfffc0080
	s_addc_u32 s1, vcc_hi, -1
	s_cmp_eq_u32 s59, 12
	s_cselect_b32 s91, s22, s1
	s_cselect_b32 s90, s23, s0
	s_cselect_b32 s1, s3, s57
	s_cselect_b32 s0, s51, s55
	v_lshl_add_u64 v[190:191], vcc, 0, v[166:167]
	s_add_i32 m0, s12, 0xc000
	ds_read_b128 v[68:71], v237
	ds_read_b128 v[72:75], v237 offset:1024
	ds_read_b128 v[76:79], v237 offset:2048
	ds_read_b128 v[80:83], v237 offset:3072
	ds_read_b128 v[174:177], v237 offset:4096
	ds_read_b128 v[178:181], v237 offset:5120
	ds_read_b128 v[182:185], v237 offset:6144
	ds_read_b128 v[186:189], v237 offset:7168
	global_load_lds_dwordx4 v[190:191], off
	v_lshl_add_u64 v[190:191], vcc, 0, v[168:169]
	s_add_i32 m0, s12, 0xe000
	s_nop 0
	global_load_lds_dwordx4 v[190:191], off
	s_waitcnt lgkmcnt(8)
	s_barrier
	s_waitcnt lgkmcnt(0)
	s_waitcnt lgkmcnt(0)
	v_mfma_f32_16x16x32_bf16 v[156:159], v[44:47], v[68:71], v[156:159]
	v_mfma_f32_16x16x32_bf16 v[132:135], v[52:55], v[68:71], v[132:135]
	v_mfma_f32_16x16x32_bf16 v[152:155], v[44:47], v[76:79], v[152:155]
	v_mfma_f32_16x16x32_bf16 v[128:131], v[52:55], v[76:79], v[128:131]
	v_mfma_f32_16x16x32_bf16 v[140:143], v[44:47], v[174:177], v[140:143]
	v_mfma_f32_16x16x32_bf16 v[104:107], v[52:55], v[174:177], v[104:107]
	v_mfma_f32_16x16x32_bf16 v[144:147], v[44:47], v[182:185], v[144:147]
	v_mfma_f32_16x16x32_bf16 v[108:111], v[52:55], v[182:185], v[108:111]
	v_mfma_f32_16x16x32_bf16 v[156:159], v[48:51], v[72:75], v[156:159]
	v_mfma_f32_16x16x32_bf16 v[132:135], v[56:59], v[72:75], v[132:135]
	v_mfma_f32_16x16x32_bf16 v[152:155], v[48:51], v[80:83], v[152:155]
	v_mfma_f32_16x16x32_bf16 v[128:131], v[56:59], v[80:83], v[128:131]
	v_mfma_f32_16x16x32_bf16 v[140:143], v[48:51], v[178:181], v[140:143]
	v_mfma_f32_16x16x32_bf16 v[104:107], v[56:59], v[178:181], v[104:107]
	v_mfma_f32_16x16x32_bf16 v[144:147], v[48:51], v[186:189], v[144:147]
	v_mfma_f32_16x16x32_bf16 v[108:111], v[56:59], v[186:189], v[108:111]
	s_barrier
	s_add_i32 s60, s20, s11
	v_lshl_add_u64 v[214:215], s[0:1], 0, v[160:161]
	s_mov_b32 m0, s60
	ds_read_b128 v[190:193], v238
	ds_read_b128 v[194:197], v238 offset:1024
	ds_read_b128 v[198:201], v238 offset:2048
	ds_read_b128 v[202:205], v238 offset:3072
	global_load_lds_dwordx4 v[214:215], off
	v_lshl_add_u64 v[216:217], s[0:1], 0, v[162:163]
	s_add_i32 m0, s60, 0x2000
	s_nop 0
	global_load_lds_dwordx4 v[216:217], off
	s_barrier
	s_waitcnt lgkmcnt(0)
	s_waitcnt lgkmcnt(0)
	v_mfma_f32_16x16x32_bf16 v[148:151], v[190:193], v[68:71], v[148:151]
	v_mfma_f32_16x16x32_bf16 v[68:71], v[198:201], v[68:71], v[124:127]
	v_mfma_f32_16x16x32_bf16 v[148:151], v[194:197], v[72:75], v[148:151]
	v_mfma_f32_16x16x32_bf16 v[68:71], v[202:205], v[72:75], v[68:71]
	v_mfma_f32_16x16x32_bf16 v[72:75], v[190:193], v[76:79], v[120:123]
	v_mfma_f32_16x16x32_bf16 v[76:79], v[198:201], v[76:79], v[112:115]
	v_mfma_f32_16x16x32_bf16 v[100:103], v[198:201], v[174:177], v[100:103]
	v_mfma_f32_16x16x32_bf16 v[112:115], v[190:193], v[182:185], v[136:139]
	v_mfma_f32_16x16x32_bf16 v[96:99], v[198:201], v[182:185], v[96:99]
	v_mfma_f32_16x16x32_bf16 v[72:75], v[194:197], v[80:83], v[72:75]
	v_mfma_f32_16x16x32_bf16 v[76:79], v[202:205], v[80:83], v[76:79]
	v_mfma_f32_16x16x32_bf16 v[80:83], v[190:193], v[174:177], v[116:119]
	v_mfma_f32_16x16x32_bf16 v[100:103], v[202:205], v[178:181], v[100:103]
	v_mfma_f32_16x16x32_bf16 v[136:139], v[194:197], v[186:189], v[112:115]
	v_mfma_f32_16x16x32_bf16 v[96:99], v[202:205], v[186:189], v[96:99]
	v_mfma_f32_16x16x32_bf16 v[80:83], v[194:197], v[178:181], v[80:83]
	s_mov_b32 m0, s12
	v_lshl_add_u64 v[218:219], s[90:91], 0, v[160:161]
	s_barrier
	ds_read_b128 v[112:115], v237 offset:16384
	ds_read_b128 v[116:119], v237 offset:17408
	ds_read_b128 v[120:123], v237 offset:18432
	ds_read_b128 v[124:127], v237 offset:19456
	ds_read_b128 v[174:177], v237 offset:20480
	ds_read_b128 v[178:181], v237 offset:21504
	ds_read_b128 v[182:185], v237 offset:22528
	ds_read_b128 v[186:189], v237 offset:23552
	global_load_lds_dwordx4 v[218:219], off
	v_lshl_add_u64 v[220:221], s[90:91], 0, v[162:163]
	s_mov_b32 m0, s13
	s_nop 0
	global_load_lds_dwordx4 v[220:221], off
	s_barrier
	s_waitcnt lgkmcnt(0)
	s_waitcnt lgkmcnt(0)
	v_mfma_f32_16x16x32_bf16 v[92:95], v[44:47], v[112:115], v[92:95]
	v_mfma_f32_16x16x32_bf16 v[40:43], v[52:55], v[112:115], v[40:43]
	v_mfma_f32_16x16x32_bf16 v[88:91], v[44:47], v[120:123], v[88:91]
	v_mfma_f32_16x16x32_bf16 v[36:39], v[52:55], v[120:123], v[36:39]
	v_mfma_f32_16x16x32_bf16 v[60:63], v[44:47], v[174:177], v[60:63]
	v_mfma_f32_16x16x32_bf16 v[8:11], v[52:55], v[174:177], v[8:11]
	v_mfma_f32_16x16x32_bf16 v[16:19], v[52:55], v[182:185], v[16:19]
	v_mfma_f32_16x16x32_bf16 v[92:95], v[48:51], v[116:119], v[92:95]
	v_mfma_f32_16x16x32_bf16 v[40:43], v[56:59], v[116:119], v[40:43]
	v_mfma_f32_16x16x32_bf16 v[88:91], v[48:51], v[124:127], v[88:91]
	v_mfma_f32_16x16x32_bf16 v[36:39], v[56:59], v[124:127], v[36:39]
	v_mfma_f32_16x16x32_bf16 v[60:63], v[48:51], v[178:181], v[60:63]
	v_mfma_f32_16x16x32_bf16 v[8:11], v[56:59], v[178:181], v[8:11]
	v_mfma_f32_16x16x32_bf16 v[44:47], v[44:47], v[182:185], v[64:67]
	v_mfma_f32_16x16x32_bf16 v[16:19], v[56:59], v[186:189], v[16:19]
	v_mfma_f32_16x16x32_bf16 v[44:47], v[48:51], v[186:189], v[44:47]
	s_barrier
	s_add_u32 s60, s0, 0x40000
	s_addc_u32 s61, s1, 0
	s_add_i32 s63, s21, s11
	v_lshl_add_u64 v[48:49], s[60:61], 0, v[160:161]
	s_mov_b32 m0, s63
	s_nop 0
	global_load_lds_dwordx4 v[48:49], off
	v_lshl_add_u64 v[48:49], s[60:61], 0, v[162:163]
	s_add_i32 m0, s63, 0x2000
	s_nop 0
	global_load_lds_dwordx4 v[48:49], off
	s_waitcnt vmcnt(6)
	s_barrier
	v_mfma_f32_16x16x32_bf16 v[28:31], v[198:201], v[112:115], v[28:31]
	v_mfma_f32_16x16x32_bf16 v[24:27], v[190:193], v[120:123], v[24:27]
	v_mfma_f32_16x16x32_bf16 v[12:15], v[198:201], v[120:123], v[12:15]
	v_mfma_f32_16x16x32_bf16 v[20:23], v[190:193], v[174:177], v[20:23]
	v_mfma_f32_16x16x32_bf16 v[4:7], v[198:201], v[174:177], v[4:7]
	v_mfma_f32_16x16x32_bf16 v[32:35], v[190:193], v[182:185], v[32:35]
	v_mfma_f32_16x16x32_bf16 v[0:3], v[198:201], v[182:185], v[0:3]
	v_mfma_f32_16x16x32_bf16 v[48:51], v[190:193], v[112:115], v[84:87]
	v_mfma_f32_16x16x32_bf16 v[28:31], v[202:205], v[116:119], v[28:31]
	v_mfma_f32_16x16x32_bf16 v[24:27], v[194:197], v[124:127], v[24:27]
	v_mfma_f32_16x16x32_bf16 v[12:15], v[202:205], v[124:127], v[12:15]
	v_mfma_f32_16x16x32_bf16 v[20:23], v[194:197], v[178:181], v[20:23]
	v_mfma_f32_16x16x32_bf16 v[4:7], v[202:205], v[178:181], v[4:7]
	v_mfma_f32_16x16x32_bf16 v[32:35], v[194:197], v[186:189], v[32:35]
	v_mfma_f32_16x16x32_bf16 v[0:3], v[202:205], v[186:189], v[0:3]
	v_mfma_f32_16x16x32_bf16 v[48:51], v[194:197], v[116:119], v[48:51]
	s_add_i32 s63, 0, 0x18000
	v_add_u32_e32 v64, s63, v232
	s_barrier
	ds_read_b128 v[52:55], v64
	ds_read_b128 v[56:59], v64 offset:1024
	ds_read_b128 v[84:87], v64 offset:2048
	ds_read_b128 v[174:177], v64 offset:3072
	s_add_u32 s60, s90, 0x40000
	s_addc_u32 s61, s91, 0
	s_mov_b32 m0, s14
	v_lshl_add_u64 v[120:121], s[60:61], 0, v[160:161]
	ds_read_b128 v[64:67], v237 offset:32768
	ds_read_b128 v[112:115], v237 offset:33792
	ds_read_b128 v[116:119], v237 offset:34816
	ds_read_b128 v[178:181], v237 offset:35840
	ds_read_b128 v[182:185], v237 offset:36864
	ds_read_b128 v[186:189], v237 offset:37888
	ds_read_b128 v[190:193], v237 offset:38912
	ds_read_b128 v[194:197], v237 offset:39936
	global_load_lds_dwordx4 v[120:121], off
	v_lshl_add_u64 v[120:121], s[60:61], 0, v[162:163]
	s_mov_b32 m0, s15
	s_nop 0
	global_load_lds_dwordx4 v[120:121], off
	s_waitcnt lgkmcnt(8)
	s_barrier
	s_waitcnt lgkmcnt(0)
	s_waitcnt lgkmcnt(0)
	v_mfma_f32_16x16x32_bf16 v[120:123], v[52:55], v[64:67], v[156:159]
	v_mfma_f32_16x16x32_bf16 v[156:159], v[56:59], v[112:115], v[120:123]
	v_mfma_f32_16x16x32_bf16 v[120:123], v[84:87], v[64:67], v[132:135]
	v_mfma_f32_16x16x32_bf16 v[132:135], v[174:177], v[112:115], v[120:123]
	v_mfma_f32_16x16x32_bf16 v[120:123], v[52:55], v[116:119], v[152:155]
	v_mfma_f32_16x16x32_bf16 v[152:155], v[56:59], v[178:181], v[120:123]
	v_mfma_f32_16x16x32_bf16 v[120:123], v[84:87], v[116:119], v[128:131]
	v_mfma_f32_16x16x32_bf16 v[128:131], v[174:177], v[178:181], v[120:123]
	v_mfma_f32_16x16x32_bf16 v[120:123], v[52:55], v[182:185], v[140:143]
	v_mfma_f32_16x16x32_bf16 v[140:143], v[56:59], v[186:189], v[120:123]
	v_mfma_f32_16x16x32_bf16 v[104:107], v[84:87], v[182:185], v[104:107]
	v_mfma_f32_16x16x32_bf16 v[120:123], v[52:55], v[190:193], v[144:147]
	v_mfma_f32_16x16x32_bf16 v[108:111], v[84:87], v[190:193], v[108:111]
	v_mfma_f32_16x16x32_bf16 v[104:107], v[174:177], v[186:189], v[104:107]
	v_mfma_f32_16x16x32_bf16 v[144:147], v[56:59], v[194:197], v[120:123]
	v_mfma_f32_16x16x32_bf16 v[108:111], v[174:177], v[194:197], v[108:111]
	s_barrier
	s_add_i32 s60, 0, 0x1c000
	s_nop 0
	v_add_u32_e32 v120, s60, v232
	s_add_i32 s61, s63, s11
	ds_read_b128 v[198:201], v120
	ds_read_b128 v[202:205], v120 offset:1024
	ds_read_b128 v[206:209], v120 offset:2048
	ds_read_b128 v[210:213], v120 offset:3072
	v_lshl_add_u64 v[120:121], v[214:215], 0, s[52:53]
	s_mov_b32 m0, s61
	s_nop 0
	global_load_lds_dwordx4 v[120:121], off
	v_lshl_add_u64 v[120:121], v[216:217], 0, s[52:53]
	s_add_i32 m0, s61, 0x2000
	s_nop 0
	global_load_lds_dwordx4 v[120:121], off
	s_barrier
	s_waitcnt lgkmcnt(0)
	s_waitcnt lgkmcnt(0)
	v_mfma_f32_16x16x32_bf16 v[120:123], v[198:201], v[64:67], v[148:151]
	v_mfma_f32_16x16x32_bf16 v[64:67], v[206:209], v[64:67], v[68:71]
	v_mfma_f32_16x16x32_bf16 v[124:127], v[210:213], v[112:115], v[64:67]
	v_mfma_f32_16x16x32_bf16 v[64:67], v[198:201], v[116:119], v[72:75]
	v_mfma_f32_16x16x32_bf16 v[148:151], v[202:205], v[112:115], v[120:123]
	v_mfma_f32_16x16x32_bf16 v[120:123], v[202:205], v[178:181], v[64:67]
	v_mfma_f32_16x16x32_bf16 v[64:67], v[206:209], v[116:119], v[76:79]
	v_mfma_f32_16x16x32_bf16 v[112:115], v[210:213], v[178:181], v[64:67]
	v_mfma_f32_16x16x32_bf16 v[64:67], v[198:201], v[182:185], v[80:83]
	v_mfma_f32_16x16x32_bf16 v[116:119], v[202:205], v[186:189], v[64:67]
	v_mfma_f32_16x16x32_bf16 v[64:67], v[206:209], v[182:185], v[100:103]
	v_mfma_f32_16x16x32_bf16 v[100:103], v[210:213], v[186:189], v[64:67]
	v_mfma_f32_16x16x32_bf16 v[64:67], v[198:201], v[190:193], v[136:139]
	v_mfma_f32_16x16x32_bf16 v[136:139], v[202:205], v[194:197], v[64:67]
	v_mfma_f32_16x16x32_bf16 v[64:67], v[206:209], v[190:193], v[96:99]
	v_mfma_f32_16x16x32_bf16 v[96:99], v[210:213], v[194:197], v[64:67]
	s_mov_b32 m0, s17
	s_nop 4
	v_lshl_add_u64 v[64:65], v[218:219], 0, s[52:53]
	s_barrier
	ds_read_b128 v[68:71], v237 offset:49152
	ds_read_b128 v[72:75], v237 offset:50176
	ds_read_b128 v[76:79], v237 offset:51200
	ds_read_b128 v[80:83], v237 offset:52224
	ds_read_b128 v[178:181], v237 offset:53248
	ds_read_b128 v[182:185], v237 offset:54272
	ds_read_b128 v[186:189], v237 offset:55296
	ds_read_b128 v[190:193], v237 offset:56320
	global_load_lds_dwordx4 v[64:65], off
	v_lshl_add_u64 v[64:65], v[220:221], 0, s[52:53]
	s_mov_b32 m0, s18
	s_nop 0
	global_load_lds_dwordx4 v[64:65], off
	s_barrier
	s_waitcnt lgkmcnt(0)
	s_waitcnt lgkmcnt(0)
	v_mfma_f32_16x16x32_bf16 v[64:67], v[52:55], v[68:71], v[92:95]
	v_mfma_f32_16x16x32_bf16 v[92:95], v[56:59], v[72:75], v[64:67]
	v_mfma_f32_16x16x32_bf16 v[40:43], v[84:87], v[68:71], v[40:43]
	v_mfma_f32_16x16x32_bf16 v[64:67], v[52:55], v[76:79], v[88:91]
	v_mfma_f32_16x16x32_bf16 v[36:39], v[84:87], v[76:79], v[36:39]
	v_mfma_f32_16x16x32_bf16 v[60:63], v[52:55], v[178:181], v[60:63]
	v_mfma_f32_16x16x32_bf16 v[8:11], v[84:87], v[178:181], v[8:11]
	v_mfma_f32_16x16x32_bf16 v[44:47], v[52:55], v[186:189], v[44:47]
	v_mfma_f32_16x16x32_bf16 v[16:19], v[84:87], v[186:189], v[16:19]
	v_mfma_f32_16x16x32_bf16 v[40:43], v[174:177], v[72:75], v[40:43]
	v_mfma_f32_16x16x32_bf16 v[88:91], v[56:59], v[80:83], v[64:67]
	v_mfma_f32_16x16x32_bf16 v[36:39], v[174:177], v[80:83], v[36:39]
	v_mfma_f32_16x16x32_bf16 v[60:63], v[56:59], v[182:185], v[60:63]
	v_mfma_f32_16x16x32_bf16 v[8:11], v[174:177], v[182:185], v[8:11]
	v_mfma_f32_16x16x32_bf16 v[64:67], v[56:59], v[190:193], v[44:47]
	v_mfma_f32_16x16x32_bf16 v[16:19], v[174:177], v[190:193], v[16:19]
	s_barrier
	s_add_u32 s0, s0, 0x40080
	s_addc_u32 s1, s1, 0
	s_add_i32 s60, s60, s11
	v_lshl_add_u64 v[44:45], s[0:1], 0, v[160:161]
	s_mov_b32 m0, s60
	s_nop 0
	global_load_lds_dwordx4 v[44:45], off
	v_lshl_add_u64 v[44:45], s[0:1], 0, v[162:163]
	s_add_i32 m0, s60, 0x2000
	s_nop 0
	global_load_lds_dwordx4 v[44:45], off
	s_waitcnt vmcnt(6)
	s_barrier
	v_mfma_f32_16x16x32_bf16 v[44:47], v[198:201], v[68:71], v[48:51]
	v_mfma_f32_16x16x32_bf16 v[28:31], v[206:209], v[68:71], v[28:31]
	v_mfma_f32_16x16x32_bf16 v[24:27], v[198:201], v[76:79], v[24:27]
	v_mfma_f32_16x16x32_bf16 v[12:15], v[206:209], v[76:79], v[12:15]
	v_mfma_f32_16x16x32_bf16 v[20:23], v[198:201], v[178:181], v[20:23]
	v_mfma_f32_16x16x32_bf16 v[4:7], v[206:209], v[178:181], v[4:7]
	v_mfma_f32_16x16x32_bf16 v[32:35], v[198:201], v[186:189], v[32:35]
	v_mfma_f32_16x16x32_bf16 v[0:3], v[206:209], v[186:189], v[0:3]
	v_mfma_f32_16x16x32_bf16 v[84:87], v[202:205], v[72:75], v[44:47]
	v_mfma_f32_16x16x32_bf16 v[28:31], v[210:213], v[72:75], v[28:31]
	v_mfma_f32_16x16x32_bf16 v[24:27], v[202:205], v[80:83], v[24:27]
	v_mfma_f32_16x16x32_bf16 v[12:15], v[210:213], v[80:83], v[12:15]
	v_mfma_f32_16x16x32_bf16 v[20:23], v[202:205], v[182:185], v[20:23]
	v_mfma_f32_16x16x32_bf16 v[4:7], v[210:213], v[182:185], v[4:7]
	v_mfma_f32_16x16x32_bf16 v[32:35], v[202:205], v[190:193], v[32:35]
	v_mfma_f32_16x16x32_bf16 v[0:3], v[210:213], v[190:193], v[0:3]
	s_add_i32 s59, s59, 2
	s_add_u32 vcc_lo, vcc_lo, 0x100
	s_addc_u32 vcc_hi, vcc_hi, 0
	s_add_u32 s55, s55, 0x100
	s_addc_u32 s57, s57, 0
	s_cmp_gt_u32 s59, 13
	s_barrier
	s_cbranch_scc0 .LBB0_703
	s_setprio 0
	v_lshl_add_u32 v164, s84, 8, v231
	v_lshl_add_u64 v[44:45], v[164:165], 2, s[34:35]
	global_load_dword v184, v[44:45], off
	v_or_b32_e32 v182, 16, v164
	v_mov_b32_e32 v183, v165
	v_lshl_add_u64 v[44:45], v[182:183], 2, s[34:35]
	global_load_dword v186, v[44:45], off
	v_or_b32_e32 v44, 32, v164
	v_mov_b32_e32 v45, v165
	v_lshl_add_u64 v[44:45], v[44:45], 2, s[34:35]
	v_or_b32_e32 v180, 48, v164
	v_mov_b32_e32 v181, v165
	global_load_dword v200, v[44:45], off
	v_lshl_add_u64 v[44:45], v[180:181], 2, s[34:35]
	v_add_u32_e32 v178, 0x80, v164
	v_mov_b32_e32 v179, v165
	global_load_dword v185, v[44:45], off
	v_lshl_add_u64 v[44:45], v[178:179], 2, s[34:35]
	v_add_u32_e32 v174, 0x90, v164
	v_mov_b32_e32 v175, v165
	global_load_dword v183, v[44:45], off
	v_lshl_add_u64 v[44:45], v[174:175], 2, s[34:35]
	global_load_dword v181, v[44:45], off
	v_add_u32_e32 v44, 0xa0, v164
	v_mov_b32_e32 v45, v165
	v_lshl_add_u64 v[44:45], v[44:45], 2, s[34:35]
	global_load_dword v175, v[44:45], off
	v_add_u32_e32 v44, 0xb0, v164
	v_mov_b32_e32 v45, v165
	v_lshl_or_b32 v176, s88, 7, v235
	v_lshl_add_u64 v[44:45], v[44:45], 2, s[34:35]
	v_ashrrev_i32_e32 v177, 31, v176
	v_readlane_b32 s44, v254, 1
	global_load_dword v179, v[44:45], off
	v_lshlrev_b64 v[44:45], 2, v[176:177]
	v_readlane_b32 s48, v254, 5
	v_readlane_b32 s49, v254, 6
	v_readlane_b32 s50, v254, 7
	v_readlane_b32 s51, v254, 8
	v_lshl_add_u64 v[48:49], s[48:49], 0, v[44:45]
	v_lshl_add_u64 v[52:53], s[96:97], 0, v[44:45]
	v_lshl_add_u64 v[56:57], s[86:87], 0, v[44:45]
	v_lshl_add_u64 v[80:81], s[50:51], 0, v[44:45]
	global_load_dwordx4 v[44:47], v[48:49], off offset:16
	global_load_dwordx4 v[68:71], v[48:49], off
	s_nop 0
	global_load_dwordx4 v[48:51], v[52:53], off offset:16
	global_load_dwordx4 v[72:75], v[52:53], off
	s_nop 0
	global_load_dwordx4 v[52:55], v[56:57], off offset:16
	global_load_dwordx4 v[76:79], v[56:57], off
	s_nop 0
	global_load_dwordx4 v[56:59], v[80:81], off offset:16
	s_nop 0
	global_load_dwordx4 v[80:83], v[80:81], off
	v_mov_b32_e32 v190, 0
	v_mov_b32_e32 v192, 0
	v_mov_b32_e32 v191, 0
	v_mov_b32_e32 v193, 0
	v_mov_b32_e32 v196, 0
	s_lshl_b32 s3, s84, 2
	v_mov_b32_e32 v198, 0
	s_add_i32 s3, s3, s10
	v_mov_b32_e32 v197, 0
	s_mul_i32 s51, s3, 6
	v_mov_b32_e32 v199, 0
	v_readlane_b32 s45, v254, 2
	v_readlane_b32 s46, v254, 3
	v_readlane_b32 s47, v254, 4
	s_waitcnt vmcnt(0)
	v_fmamk_f32 v177, v184, 0x3a800000, v239
	v_cmp_gt_f32_e32 vcc, s33, v177
	v_mul_f32_e32 v184, 0x4b800000, v177
	s_nop 0
	v_cndmask_b32_e32 v177, v177, v184, vcc
	v_rsq_f32_e32 v177, v177
	s_nop 0
	v_mul_f32_e32 v184, 0x45800000, v177
	v_cndmask_b32_e32 v188, v177, v184, vcc
	v_fmamk_f32 v177, v186, 0x3a800000, v239
	v_cmp_gt_f32_e32 vcc, s33, v177
	v_mul_f32_e32 v184, 0x4b800000, v177
	v_pk_mul_f32 v[186:187], v[156:157], v[188:189] op_sel_hi:[1,0]
	v_cndmask_b32_e32 v177, v177, v184, vcc
	v_rsq_f32_e32 v177, v177
	v_cndmask_b32_e64 v156, v186, 0, s[38:39]
	v_pk_mul_f32 v[194:195], v[158:159], v[188:189] op_sel_hi:[1,0]
	v_mul_f32_e32 v184, 0x45800000, v177
	v_cndmask_b32_e32 v184, v177, v184, vcc
	v_mov_b32_dpp v190, v156 row_ror:1 row_mask:0xf bank_mask:0xf
	v_pk_mul_f32 v[156:157], v[152:153], v[184:185] op_sel_hi:[1,0]
	v_pk_mul_f32 v[158:159], v[154:155], v[184:185] op_sel_hi:[1,0]
	v_cndmask_b32_e64 v152, v186, v156, s[42:43]
	v_add_u32_e32 v155, s51, v234
	s_nop 0
	v_mov_b32_dpp v192, v152 row_ror:15 row_mask:0xf bank_mask:0xf
	v_cndmask_b32_e64 v152, v187, 0, s[38:39]
	s_nop 1
	v_mov_b32_dpp v191, v152 row_ror:1 row_mask:0xf bank_mask:0xf
	v_cndmask_b32_e64 v152, v187, v157, s[42:43]
	s_nop 1
	v_mov_b32_dpp v193, v152 row_ror:15 row_mask:0xf bank_mask:0xf
	v_cndmask_b32_e64 v152, v194, 0, s[38:39]
	s_nop 1
	v_mov_b32_dpp v196, v152 row_ror:1 row_mask:0xf bank_mask:0xf
	v_cndmask_b32_e64 v152, v194, v158, s[42:43]
	s_nop 1
	v_mov_b32_dpp v198, v152 row_ror:15 row_mask:0xf bank_mask:0xf
	v_cndmask_b32_e64 v152, v195, 0, s[38:39]
	s_nop 1
	v_mov_b32_dpp v197, v152 row_ror:1 row_mask:0xf bank_mask:0xf
	v_cndmask_b32_e64 v152, v195, v159, s[42:43]
	s_nop 1
	v_mov_b32_dpp v199, v152 row_ror:15 row_mask:0xf bank_mask:0xf
	s_and_saveexec_b64 s[0:1], s[70:71]
	s_cbranch_execz .LBB0_706
	v_mad_u64_u32 v[202:203], s[22:23], v155, s65, v[176:177]
	v_mov_b32_e32 v203, v165
	v_cvt_pk_bf16_f32 v152, v186, v187
	v_cvt_pk_bf16_f32 v153, v194, v195
	v_lshl_add_u64 v[202:203], v[202:203], 1, s[30:31]
	global_store_dwordx2 v[202:203], v[152:153], off

.LBB0_868:
	s_cmp_lt_i32 s82, 14
	s_cselect_b64 s[0:1], -1, 0
	s_and_b64 s[0:1], s[0:1], s[2:3]
	s_andn2_b64 vcc, exec, s[0:1]
	s_cbranch_vccnz .LBB0_893
	s_mov_b64 s[0:1], 0
	v_readlane_b32 s2, v254, 0
	v_mov_b32_e32 v0, v230
	s_cmpk_gt_i32 s2, 0x3ff
	v_readfirstlane_b32 s16, v230
	s_cbranch_scc1 .LBB0_893
	s_mov_b32 s41, s2
	s_ashr_i32 s17, s41, 31
	s_lshr_b32 s2, s17, 29
	s_add_i32 s4, s41, s2
	s_and_b32 s2, s4, -8
	s_sub_i32 s6, s41, s2
	s_cmp_gt_i32 s6, -1
	s_cbranch_scc0 .LBB0_872
	s_lshl_b32 s7, s6, 7
	s_ashr_i32 s2, s4, 3
	s_cbranch_execz .LBB0_873
	s_branch .LBB0_874
	s_nop 0
	s_nop 0
	s_nop 0
	s_nop 0
	s_nop 0
	s_nop 0
	s_nop 0
	s_nop 0
	s_nop 0
	s_nop 0
	s_nop 0

.LBB0_888:
	s_cmp_ge_u32 s23, 0x1000
	s_cbranch_scc0 .Lsp_5
	s_setprio 1
.Lsp_5:
	ds_read_b128 v[140:143], v149
	ds_read_b128 v[152:155], v149 offset:1024
	ds_read_b128 v[156:159], v149 offset:2048
	ds_read_b128 v[160:163], v149 offset:3072
	s_add_u32 s10, s2, 0x100
	s_addc_u32 s11, s3, 0
	s_cmp_eq_u32 s39, 40
	s_cselect_b32 s15, s7, s11
	s_cselect_b32 s14, s6, s10
	s_cselect_b32 s13, s5, s38
	s_cselect_b32 s12, s4, s37
	v_lshl_add_u64 v[144:145], s[2:3], 0, v[132:133]
	s_add_i32 m0, s23, 0xc000
	ds_read_b128 v[164:167], v150
	ds_read_b128 v[168:171], v150 offset:1024
	ds_read_b128 v[172:175], v150 offset:2048
	ds_read_b128 v[176:179], v150 offset:3072
	ds_read_b128 v[180:183], v150 offset:4096
	ds_read_b128 v[184:187], v150 offset:5120
	ds_read_b128 v[188:191], v150 offset:6144
	ds_read_b128 v[192:195], v150 offset:7168
	global_load_lds_dwordx4 v[144:145], off
	v_lshl_add_u64 v[144:145], s[2:3], 0, v[134:135]
	s_add_i32 m0, s23, 0xe000
	s_nop 0
	global_load_lds_dwordx4 v[144:145], off
	s_waitcnt lgkmcnt(8)
	s_barrier
	s_waitcnt lgkmcnt(0)
	s_waitcnt lgkmcnt(0)
	v_mfma_f32_16x16x32_bf16 v[124:127], v[140:143], v[164:167], v[124:127]
	v_mfma_f32_16x16x32_bf16 v[120:123], v[156:159], v[164:167], v[120:123]
	v_mfma_f32_16x16x32_bf16 v[116:119], v[140:143], v[172:175], v[116:119]
	v_mfma_f32_16x16x32_bf16 v[112:115], v[156:159], v[172:175], v[112:115]
	v_mfma_f32_16x16x32_bf16 v[92:95], v[140:143], v[180:183], v[92:95]
	v_mfma_f32_16x16x32_bf16 v[88:91], v[156:159], v[180:183], v[88:91]
	v_mfma_f32_16x16x32_bf16 v[84:87], v[140:143], v[188:191], v[84:87]
	v_mfma_f32_16x16x32_bf16 v[80:83], v[156:159], v[188:191], v[80:83]
	v_mfma_f32_16x16x32_bf16 v[124:127], v[152:155], v[168:171], v[124:127]
	v_mfma_f32_16x16x32_bf16 v[120:123], v[160:163], v[168:171], v[120:123]
	v_mfma_f32_16x16x32_bf16 v[116:119], v[152:155], v[176:179], v[116:119]
	v_mfma_f32_16x16x32_bf16 v[112:115], v[160:163], v[176:179], v[112:115]
	v_mfma_f32_16x16x32_bf16 v[92:95], v[152:155], v[184:187], v[92:95]
	v_mfma_f32_16x16x32_bf16 v[88:91], v[160:163], v[184:187], v[88:91]
	v_mfma_f32_16x16x32_bf16 v[84:87], v[152:155], v[192:195], v[84:87]
	v_mfma_f32_16x16x32_bf16 v[80:83], v[160:163], v[192:195], v[80:83]
	s_barrier
	s_add_i32 s2, s30, s22
	v_lshl_add_u64 v[144:145], s[12:13], 0, v[128:129]
	s_mov_b32 m0, s2
	ds_read_b128 v[196:199], v151
	ds_read_b128 v[200:203], v151 offset:1024
	ds_read_b128 v[204:207], v151 offset:2048
	ds_read_b128 v[208:211], v151 offset:3072
	global_load_lds_dwordx4 v[144:145], off
	v_lshl_add_u64 v[212:213], s[12:13], 0, v[130:131]
	s_add_i32 m0, s2, 0x2000
	s_nop 0
	global_load_lds_dwordx4 v[212:213], off
	s_barrier
	s_waitcnt lgkmcnt(0)
	s_waitcnt lgkmcnt(0)
	v_mfma_f32_16x16x32_bf16 v[108:111], v[196:199], v[164:167], v[108:111]
	v_mfma_f32_16x16x32_bf16 v[104:107], v[204:207], v[164:167], v[104:107]
	v_mfma_f32_16x16x32_bf16 v[100:103], v[196:199], v[172:175], v[100:103]
	v_mfma_f32_16x16x32_bf16 v[96:99], v[204:207], v[172:175], v[96:99]
	v_mfma_f32_16x16x32_bf16 v[76:79], v[196:199], v[180:183], v[76:79]
	v_mfma_f32_16x16x32_bf16 v[72:75], v[204:207], v[180:183], v[72:75]
	v_mfma_f32_16x16x32_bf16 v[68:71], v[196:199], v[188:191], v[68:71]
	v_mfma_f32_16x16x32_bf16 v[64:67], v[204:207], v[188:191], v[64:67]
	v_mfma_f32_16x16x32_bf16 v[108:111], v[200:203], v[168:171], v[108:111]
	v_mfma_f32_16x16x32_bf16 v[104:107], v[208:211], v[168:171], v[104:107]
	v_mfma_f32_16x16x32_bf16 v[100:103], v[200:203], v[176:179], v[100:103]
	v_mfma_f32_16x16x32_bf16 v[96:99], v[208:211], v[176:179], v[96:99]
	v_mfma_f32_16x16x32_bf16 v[76:79], v[200:203], v[184:187], v[76:79]
	v_mfma_f32_16x16x32_bf16 v[72:75], v[208:211], v[184:187], v[72:75]
	v_mfma_f32_16x16x32_bf16 v[68:71], v[200:203], v[192:195], v[68:71]
	v_mfma_f32_16x16x32_bf16 v[64:67], v[208:211], v[192:195], v[64:67]
	s_mov_b32 m0, s23
	v_lshl_add_u64 v[214:215], s[14:15], 0, v[128:129]
	s_barrier
	ds_read_b128 v[164:167], v150 offset:16384
	ds_read_b128 v[168:171], v150 offset:17408
	ds_read_b128 v[172:175], v150 offset:18432
	ds_read_b128 v[176:179], v150 offset:19456
	ds_read_b128 v[180:183], v150 offset:20480
	ds_read_b128 v[184:187], v150 offset:21504
	ds_read_b128 v[188:191], v150 offset:22528
	ds_read_b128 v[192:195], v150 offset:23552
	global_load_lds_dwordx4 v[214:215], off
	v_lshl_add_u64 v[216:217], s[14:15], 0, v[130:131]
	s_mov_b32 m0, s24
	s_nop 0
	global_load_lds_dwordx4 v[216:217], off
	s_barrier
	s_waitcnt lgkmcnt(0)
	s_waitcnt lgkmcnt(0)
	v_mfma_f32_16x16x32_bf16 v[60:63], v[140:143], v[164:167], v[60:63]
	v_mfma_f32_16x16x32_bf16 v[56:59], v[156:159], v[164:167], v[56:59]
	v_mfma_f32_16x16x32_bf16 v[52:55], v[140:143], v[172:175], v[52:55]
	v_mfma_f32_16x16x32_bf16 v[48:51], v[156:159], v[172:175], v[48:51]
	v_mfma_f32_16x16x32_bf16 v[28:31], v[140:143], v[180:183], v[28:31]
	v_mfma_f32_16x16x32_bf16 v[24:27], v[156:159], v[180:183], v[24:27]
	v_mfma_f32_16x16x32_bf16 v[16:19], v[140:143], v[188:191], v[16:19]
	v_mfma_f32_16x16x32_bf16 v[8:11], v[156:159], v[188:191], v[8:11]
	v_mfma_f32_16x16x32_bf16 v[60:63], v[152:155], v[168:171], v[60:63]
	v_mfma_f32_16x16x32_bf16 v[56:59], v[160:163], v[168:171], v[56:59]
	v_mfma_f32_16x16x32_bf16 v[52:55], v[152:155], v[176:179], v[52:55]
	v_mfma_f32_16x16x32_bf16 v[48:51], v[160:163], v[176:179], v[48:51]
	v_mfma_f32_16x16x32_bf16 v[28:31], v[152:155], v[184:187], v[28:31]
	v_mfma_f32_16x16x32_bf16 v[24:27], v[160:163], v[184:187], v[24:27]
	v_mfma_f32_16x16x32_bf16 v[16:19], v[152:155], v[192:195], v[16:19]
	v_mfma_f32_16x16x32_bf16 v[8:11], v[160:163], v[192:195], v[8:11]
	s_barrier
	s_add_u32 s2, s12, 0xb0000
	s_addc_u32 s3, s13, 0
	s_add_i32 s40, s31, s22
	v_lshl_add_u64 v[140:141], s[2:3], 0, v[128:129]
	s_mov_b32 m0, s40
	s_nop 0
	global_load_lds_dwordx4 v[140:141], off
	v_lshl_add_u64 v[140:141], s[2:3], 0, v[130:131]
	s_add_i32 m0, s40, 0x2000
	s_nop 0
	global_load_lds_dwordx4 v[140:141], off
	s_waitcnt vmcnt(6)
	s_barrier
	v_mfma_f32_16x16x32_bf16 v[44:47], v[196:199], v[164:167], v[44:47]
	v_mfma_f32_16x16x32_bf16 v[40:43], v[204:207], v[164:167], v[40:43]
	v_mfma_f32_16x16x32_bf16 v[36:39], v[196:199], v[172:175], v[36:39]
	v_mfma_f32_16x16x32_bf16 v[32:35], v[204:207], v[172:175], v[32:35]
	v_mfma_f32_16x16x32_bf16 v[20:23], v[196:199], v[180:183], v[20:23]
	v_mfma_f32_16x16x32_bf16 v[12:15], v[204:207], v[180:183], v[12:15]
	v_mfma_f32_16x16x32_bf16 v[4:7], v[196:199], v[188:191], v[4:7]
	v_mfma_f32_16x16x32_bf16 v[0:3], v[204:207], v[188:191], v[0:3]
	v_mfma_f32_16x16x32_bf16 v[44:47], v[200:203], v[168:171], v[44:47]
	v_mfma_f32_16x16x32_bf16 v[40:43], v[208:211], v[168:171], v[40:43]
	v_mfma_f32_16x16x32_bf16 v[36:39], v[200:203], v[176:179], v[36:39]
	v_mfma_f32_16x16x32_bf16 v[32:35], v[208:211], v[176:179], v[32:35]
	v_mfma_f32_16x16x32_bf16 v[20:23], v[200:203], v[184:187], v[20:23]
	v_mfma_f32_16x16x32_bf16 v[12:15], v[208:211], v[184:187], v[12:15]
	v_mfma_f32_16x16x32_bf16 v[4:7], v[200:203], v[192:195], v[4:7]
	v_mfma_f32_16x16x32_bf16 v[0:3], v[208:211], v[192:195], v[0:3]
	s_add_i32 s40, 0, 0x18000
	v_add_u32_e32 v160, s40, v147
	s_barrier
	ds_read_b128 v[140:143], v160
	ds_read_b128 v[152:155], v160 offset:1024
	ds_read_b128 v[156:159], v160 offset:2048
	ds_read_b128 v[160:163], v160 offset:3072
	s_add_u32 s2, s14, 0xb0000
	s_addc_u32 s3, s15, 0
	s_mov_b32 m0, s25
	v_lshl_add_u64 v[196:197], s[2:3], 0, v[128:129]
	ds_read_b128 v[164:167], v150 offset:32768
	ds_read_b128 v[168:171], v150 offset:33792
	ds_read_b128 v[172:175], v150 offset:34816
	ds_read_b128 v[176:179], v150 offset:35840
	ds_read_b128 v[180:183], v150 offset:36864
	ds_read_b128 v[184:187], v150 offset:37888
	ds_read_b128 v[188:191], v150 offset:38912
	ds_read_b128 v[192:195], v150 offset:39936
	global_load_lds_dwordx4 v[196:197], off
	v_lshl_add_u64 v[196:197], s[2:3], 0, v[130:131]
	s_mov_b32 m0, s26
	s_nop 0
	global_load_lds_dwordx4 v[196:197], off
	s_waitcnt lgkmcnt(8)
	s_barrier
	s_waitcnt lgkmcnt(0)
	s_waitcnt lgkmcnt(0)
	v_mfma_f32_16x16x32_bf16 v[124:127], v[140:143], v[164:167], v[124:127]
	v_mfma_f32_16x16x32_bf16 v[120:123], v[156:159], v[164:167], v[120:123]
	v_mfma_f32_16x16x32_bf16 v[116:119], v[140:143], v[172:175], v[116:119]
	v_mfma_f32_16x16x32_bf16 v[112:115], v[156:159], v[172:175], v[112:115]
	v_mfma_f32_16x16x32_bf16 v[92:95], v[140:143], v[180:183], v[92:95]
	v_mfma_f32_16x16x32_bf16 v[88:91], v[156:159], v[180:183], v[88:91]
	v_mfma_f32_16x16x32_bf16 v[84:87], v[140:143], v[188:191], v[84:87]
	v_mfma_f32_16x16x32_bf16 v[80:83], v[156:159], v[188:191], v[80:83]
	v_mfma_f32_16x16x32_bf16 v[124:127], v[152:155], v[168:171], v[124:127]
	v_mfma_f32_16x16x32_bf16 v[120:123], v[160:163], v[168:171], v[120:123]
	v_mfma_f32_16x16x32_bf16 v[116:119], v[152:155], v[176:179], v[116:119]
	v_mfma_f32_16x16x32_bf16 v[112:115], v[160:163], v[176:179], v[112:115]
	v_mfma_f32_16x16x32_bf16 v[92:95], v[152:155], v[184:187], v[92:95]
	v_mfma_f32_16x16x32_bf16 v[88:91], v[160:163], v[184:187], v[88:91]
	v_mfma_f32_16x16x32_bf16 v[84:87], v[152:155], v[192:195], v[84:87]
	v_mfma_f32_16x16x32_bf16 v[80:83], v[160:163], v[192:195], v[80:83]
	s_barrier
	s_add_i32 s14, 0, 0x1c000
	s_add_i32 s2, s40, s22
	v_add_u32_e32 v208, s14, v147
	v_lshl_add_u64 v[144:145], v[144:145], 0, s[8:9]
	s_mov_b32 m0, s2
	ds_read_b128 v[196:199], v208
	ds_read_b128 v[200:203], v208 offset:1024
	ds_read_b128 v[204:207], v208 offset:2048
	ds_read_b128 v[208:211], v208 offset:3072
	global_load_lds_dwordx4 v[144:145], off
	v_lshl_add_u64 v[144:145], v[212:213], 0, s[8:9]
	s_add_i32 m0, s2, 0x2000
	s_nop 0
	global_load_lds_dwordx4 v[144:145], off
	s_barrier
	s_waitcnt lgkmcnt(0)
	s_waitcnt lgkmcnt(0)
	v_mfma_f32_16x16x32_bf16 v[108:111], v[196:199], v[164:167], v[108:111]
	v_mfma_f32_16x16x32_bf16 v[104:107], v[204:207], v[164:167], v[104:107]
	v_mfma_f32_16x16x32_bf16 v[100:103], v[196:199], v[172:175], v[100:103]
	v_mfma_f32_16x16x32_bf16 v[96:99], v[204:207], v[172:175], v[96:99]
	v_mfma_f32_16x16x32_bf16 v[76:79], v[196:199], v[180:183], v[76:79]
	v_mfma_f32_16x16x32_bf16 v[72:75], v[204:207], v[180:183], v[72:75]
	v_mfma_f32_16x16x32_bf16 v[68:71], v[196:199], v[188:191], v[68:71]
	v_mfma_f32_16x16x32_bf16 v[64:67], v[204:207], v[188:191], v[64:67]
	v_mfma_f32_16x16x32_bf16 v[108:111], v[200:203], v[168:171], v[108:111]
	v_mfma_f32_16x16x32_bf16 v[104:107], v[208:211], v[168:171], v[104:107]
	v_mfma_f32_16x16x32_bf16 v[100:103], v[200:203], v[176:179], v[100:103]
	v_mfma_f32_16x16x32_bf16 v[96:99], v[208:211], v[176:179], v[96:99]
	v_mfma_f32_16x16x32_bf16 v[76:79], v[200:203], v[184:187], v[76:79]
	v_mfma_f32_16x16x32_bf16 v[72:75], v[208:211], v[184:187], v[72:75]
	v_mfma_f32_16x16x32_bf16 v[68:71], v[200:203], v[192:195], v[68:71]
	v_mfma_f32_16x16x32_bf16 v[64:67], v[208:211], v[192:195], v[64:67]
	s_mov_b32 m0, s28
	v_lshl_add_u64 v[144:145], v[214:215], 0, s[8:9]
	s_barrier
	ds_read_b128 v[164:167], v150 offset:49152
	ds_read_b128 v[168:171], v150 offset:50176
	ds_read_b128 v[172:175], v150 offset:51200
	ds_read_b128 v[176:179], v150 offset:52224
	ds_read_b128 v[180:183], v150 offset:53248
	ds_read_b128 v[184:187], v150 offset:54272
	ds_read_b128 v[188:191], v150 offset:55296
	ds_read_b128 v[192:195], v150 offset:56320
	global_load_lds_dwordx4 v[144:145], off
	v_lshl_add_u64 v[144:145], v[216:217], 0, s[8:9]
	s_mov_b32 m0, s29
	s_nop 0
	global_load_lds_dwordx4 v[144:145], off
	s_barrier
	s_waitcnt lgkmcnt(0)
	s_waitcnt lgkmcnt(0)
	v_mfma_f32_16x16x32_bf16 v[60:63], v[140:143], v[164:167], v[60:63]
	v_mfma_f32_16x16x32_bf16 v[56:59], v[156:159], v[164:167], v[56:59]
	v_mfma_f32_16x16x32_bf16 v[52:55], v[140:143], v[172:175], v[52:55]
	v_mfma_f32_16x16x32_bf16 v[48:51], v[156:159], v[172:175], v[48:51]
	v_mfma_f32_16x16x32_bf16 v[28:31], v[140:143], v[180:183], v[28:31]
	v_mfma_f32_16x16x32_bf16 v[24:27], v[156:159], v[180:183], v[24:27]
	v_mfma_f32_16x16x32_bf16 v[16:19], v[140:143], v[188:191], v[16:19]
	v_mfma_f32_16x16x32_bf16 v[8:11], v[156:159], v[188:191], v[8:11]
	v_mfma_f32_16x16x32_bf16 v[60:63], v[152:155], v[168:171], v[60:63]
	v_mfma_f32_16x16x32_bf16 v[56:59], v[160:163], v[168:171], v[56:59]
	v_mfma_f32_16x16x32_bf16 v[52:55], v[152:155], v[176:179], v[52:55]
	v_mfma_f32_16x16x32_bf16 v[48:51], v[160:163], v[176:179], v[48:51]
	v_mfma_f32_16x16x32_bf16 v[28:31], v[152:155], v[184:187], v[28:31]
	v_mfma_f32_16x16x32_bf16 v[24:27], v[160:163], v[184:187], v[24:27]
	v_mfma_f32_16x16x32_bf16 v[16:19], v[152:155], v[192:195], v[16:19]
	v_mfma_f32_16x16x32_bf16 v[8:11], v[160:163], v[192:195], v[8:11]
	s_barrier
	s_add_u32 s2, s12, 0xb0080
	s_addc_u32 s3, s13, 0
	s_add_i32 s12, s14, s22
	v_lshl_add_u64 v[140:141], s[2:3], 0, v[128:129]
	s_mov_b32 m0, s12
	s_nop 0
	global_load_lds_dwordx4 v[140:141], off
	v_lshl_add_u64 v[140:141], s[2:3], 0, v[130:131]
	s_add_i32 m0, s12, 0x2000
	s_nop 0
	global_load_lds_dwordx4 v[140:141], off
	s_waitcnt vmcnt(6)
	s_barrier
	v_mfma_f32_16x16x32_bf16 v[44:47], v[196:199], v[164:167], v[44:47]
	v_mfma_f32_16x16x32_bf16 v[40:43], v[204:207], v[164:167], v[40:43]
	v_mfma_f32_16x16x32_bf16 v[36:39], v[196:199], v[172:175], v[36:39]
	v_mfma_f32_16x16x32_bf16 v[32:35], v[204:207], v[172:175], v[32:35]
	v_mfma_f32_16x16x32_bf16 v[20:23], v[196:199], v[180:183], v[20:23]
	v_mfma_f32_16x16x32_bf16 v[12:15], v[204:207], v[180:183], v[12:15]
	v_mfma_f32_16x16x32_bf16 v[4:7], v[196:199], v[188:191], v[4:7]
	v_mfma_f32_16x16x32_bf16 v[0:3], v[204:207], v[188:191], v[0:3]
	v_mfma_f32_16x16x32_bf16 v[44:47], v[200:203], v[168:171], v[44:47]
	v_mfma_f32_16x16x32_bf16 v[40:43], v[208:211], v[168:171], v[40:43]
	v_mfma_f32_16x16x32_bf16 v[36:39], v[200:203], v[176:179], v[36:39]
	v_mfma_f32_16x16x32_bf16 v[32:35], v[208:211], v[176:179], v[32:35]
	v_mfma_f32_16x16x32_bf16 v[20:23], v[200:203], v[184:187], v[20:23]
	v_mfma_f32_16x16x32_bf16 v[12:15], v[208:211], v[184:187], v[12:15]
	v_mfma_f32_16x16x32_bf16 v[4:7], v[200:203], v[192:195], v[4:7]
	v_mfma_f32_16x16x32_bf16 v[0:3], v[208:211], v[192:195], v[0:3]
	s_add_i32 s39, s39, 2
	s_add_u32 s37, s37, 0x100
	s_addc_u32 s38, s38, 0
	s_cmp_gt_u32 s39, 41
	s_mov_b64 s[2:3], s[10:11]
	s_barrier
	s_cbranch_scc0 .LBB0_888
	s_setprio 0
	v_lshl_or_b32 v140, s36, 8, v148
	v_lshl_add_u32 v144, s35, 8, v146
	v_ashrrev_i32_e32 v141, 31, v140
	v_lshlrev_b64 v[140:141], 2, v[140:141]
	v_ashrrev_i32_e32 v145, 31, v144
	v_lshl_add_u64 v[142:143], s[78:79], 0, v[140:141]
	v_lshlrev_b64 v[184:185], 12, v[144:145]
	v_lshl_add_u64 v[164:165], v[142:143], 0, v[184:185]
	v_or_b32_e32 v168, 16, v144
	global_load_dwordx4 v[152:155], v[164:165], off offset:16
	global_load_dwordx4 v[156:159], v[164:165], off
	global_load_dwordx4 v[160:163], v[164:165], off offset:144
	s_nop 0
	global_load_dwordx4 v[164:167], v[164:165], off offset:128
	v_ashrrev_i32_e32 v169, 31, v168
	v_lshlrev_b64 v[186:187], 12, v[168:169]
	v_lshl_add_u64 v[180:181], v[142:143], 0, v[186:187]
	global_load_dwordx4 v[168:171], v[180:181], off offset:16
	global_load_dwordx4 v[172:175], v[180:181], off
	global_load_dwordx4 v[176:179], v[180:181], off offset:144
	s_nop 0
	global_load_dwordx4 v[180:183], v[180:181], off offset:128
	s_and_b64 vcc, exec, s[0:1]
	s_mov_b32 s36, s34
	s_mov_b32 s35, s33
	s_mov_b64 s[10:11], s[4:5]
	s_mov_b64 s[2:3], s[6:7]
	s_waitcnt vmcnt(0)
	v_pk_add_f32 v[120:121], v[120:121], v[152:153]
	v_lshl_add_u64 v[152:153], s[78:79], 0, v[184:185]
	v_pk_add_f32 v[126:127], v[126:127], v[158:159]
	v_pk_add_f32 v[124:125], v[124:125], v[156:157]
	v_pk_add_f32 v[108:109], v[108:109], v[164:165]
	v_lshl_add_u64 v[152:153], v[152:153], 0, v[140:141]
	v_pk_add_f32 v[122:123], v[122:123], v[154:155]
	v_pk_add_f32 v[110:111], v[110:111], v[166:167]
	v_pk_add_f32 v[106:107], v[106:107], v[162:163]
	v_pk_add_f32 v[104:105], v[104:105], v[160:161]
	global_store_dwordx4 v[152:153], v[124:127], off nt
	global_store_dwordx4 v[152:153], v[120:123], off offset:16 nt
	global_store_dwordx4 v[152:153], v[108:111], off offset:128 nt
	global_store_dwordx4 v[152:153], v[104:107], off offset:144 nt
	v_pk_add_f32 v[96:97], v[96:97], v[176:177]
	v_pk_add_f32 v[108:109], v[112:113], v[168:169]
	v_lshl_add_u64 v[112:113], s[78:79], 0, v[186:187]
	v_pk_add_f32 v[106:107], v[118:119], v[174:175]
	v_pk_add_f32 v[104:105], v[116:117], v[172:173]
	v_lshl_add_u64 v[112:113], v[112:113], 0, v[140:141]
	v_pk_add_f32 v[110:111], v[114:115], v[170:171]
	v_pk_add_f32 v[102:103], v[102:103], v[182:183]
	v_pk_add_f32 v[100:101], v[100:101], v[180:181]
	v_pk_add_f32 v[98:99], v[98:99], v[178:179]
	global_store_dwordx4 v[112:113], v[104:107], off nt
	global_store_dwordx4 v[112:113], v[108:111], off offset:16 nt
	global_store_dwordx4 v[112:113], v[100:103], off offset:128 nt
	global_store_dwordx4 v[112:113], v[96:99], off offset:144 nt
	v_or_b32_e32 v112, 48, v144
	v_ashrrev_i32_e32 v113, 31, v112
	v_or_b32_e32 v96, 32, v144
	v_ashrrev_i32_e32 v97, 31, v96
	v_lshlrev_b64 v[152:153], 12, v[96:97]
	v_lshl_add_u64 v[108:109], v[142:143], 0, v[152:153]
	global_load_dwordx4 v[96:99], v[108:109], off offset:16
	global_load_dwordx4 v[100:103], v[108:109], off
	global_load_dwordx4 v[104:107], v[108:109], off offset:144
	s_nop 0
	global_load_dwordx4 v[108:111], v[108:109], off offset:128
	v_lshlrev_b64 v[154:155], 12, v[112:113]
	v_lshl_add_u64 v[124:125], v[142:143], 0, v[154:155]
	global_load_dwordx4 v[112:115], v[124:125], off offset:16
	global_load_dwordx4 v[116:119], v[124:125], off
	global_load_dwordx4 v[120:123], v[124:125], off offset:144
	s_nop 0
	global_load_dwordx4 v[124:127], v[124:125], off offset:128
	s_waitcnt vmcnt(0)
	v_pk_add_f32 v[88:89], v[88:89], v[96:97]
	v_lshl_add_u64 v[96:97], s[78:79], 0, v[152:153]
	v_pk_add_f32 v[94:95], v[94:95], v[102:103]
	v_pk_add_f32 v[92:93], v[92:93], v[100:101]
	v_pk_add_f32 v[76:77], v[76:77], v[108:109]
	v_lshl_add_u64 v[96:97], v[96:97], 0, v[140:141]
	v_pk_add_f32 v[90:91], v[90:91], v[98:99]
	v_pk_add_f32 v[78:79], v[78:79], v[110:111]
	v_pk_add_f32 v[74:75], v[74:75], v[106:107]
	v_pk_add_f32 v[72:73], v[72:73], v[104:105]
	global_store_dwordx4 v[96:97], v[92:95], off nt
	global_store_dwordx4 v[96:97], v[88:91], off offset:16 nt
	global_store_dwordx4 v[96:97], v[76:79], off offset:128 nt
	global_store_dwordx4 v[96:97], v[72:75], off offset:144 nt
	v_pk_add_f32 v[64:65], v[64:65], v[120:121]
	v_pk_add_f32 v[76:77], v[80:81], v[112:113]
	v_lshl_add_u64 v[80:81], s[78:79], 0, v[154:155]
	v_pk_add_f32 v[74:75], v[86:87], v[118:119]
	v_pk_add_f32 v[72:73], v[84:85], v[116:117]
	v_lshl_add_u64 v[80:81], v[80:81], 0, v[140:141]
	v_pk_add_f32 v[78:79], v[82:83], v[114:115]
	v_pk_add_f32 v[70:71], v[70:71], v[126:127]
	v_pk_add_f32 v[68:69], v[68:69], v[124:125]
	v_pk_add_f32 v[66:67], v[66:67], v[122:123]
	global_store_dwordx4 v[80:81], v[72:75], off nt
	global_store_dwordx4 v[80:81], v[76:79], off offset:16 nt
	global_store_dwordx4 v[80:81], v[68:71], off offset:128 nt
	global_store_dwordx4 v[80:81], v[64:67], off offset:144 nt
	s_nop 1
	v_add_u32_e32 v64, 0x80, v144
	v_ashrrev_i32_e32 v65, 31, v64
	v_lshlrev_b64 v[96:97], 12, v[64:65]
	v_lshl_add_u64 v[80:81], v[142:143], 0, v[96:97]
	global_load_dwordx4 v[64:67], v[80:81], off offset:16
	global_load_dwordx4 v[68:71], v[80:81], off
	global_load_dwordx4 v[72:75], v[80:81], off offset:144
	global_load_dwordx4 v[76:79], v[80:81], off offset:128
	v_add_u32_e32 v80, 0x90, v144
	v_ashrrev_i32_e32 v81, 31, v80
	v_lshlrev_b64 v[98:99], 12, v[80:81]
	v_lshl_add_u64 v[100:101], v[142:143], 0, v[98:99]
	global_load_dwordx4 v[80:83], v[100:101], off offset:16
	global_load_dwordx4 v[84:87], v[100:101], off
	global_load_dwordx4 v[88:91], v[100:101], off offset:144
	global_load_dwordx4 v[92:95], v[100:101], off offset:128
	s_waitcnt vmcnt(0)
	v_pk_add_f32 v[56:57], v[56:57], v[64:65]
	v_lshl_add_u64 v[64:65], s[78:79], 0, v[96:97]
	v_pk_add_f32 v[62:63], v[62:63], v[70:71]
	v_pk_add_f32 v[60:61], v[60:61], v[68:69]
	v_pk_add_f32 v[44:45], v[44:45], v[76:77]
	v_lshl_add_u64 v[64:65], v[64:65], 0, v[140:141]
	v_pk_add_f32 v[58:59], v[58:59], v[66:67]
	v_pk_add_f32 v[46:47], v[46:47], v[78:79]
	v_pk_add_f32 v[42:43], v[42:43], v[74:75]
	v_pk_add_f32 v[40:41], v[40:41], v[72:73]
	global_store_dwordx4 v[64:65], v[60:63], off nt
	global_store_dwordx4 v[64:65], v[56:59], off offset:16 nt
	global_store_dwordx4 v[64:65], v[44:47], off offset:128 nt
	global_store_dwordx4 v[64:65], v[40:43], off offset:144 nt
	v_pk_add_f32 v[32:33], v[32:33], v[88:89]
	v_pk_add_f32 v[44:45], v[48:49], v[80:81]
	v_lshl_add_u64 v[48:49], s[78:79], 0, v[98:99]
	v_pk_add_f32 v[42:43], v[54:55], v[86:87]
	v_pk_add_f32 v[40:41], v[52:53], v[84:85]
	v_lshl_add_u64 v[48:49], v[48:49], 0, v[140:141]
	v_pk_add_f32 v[46:47], v[50:51], v[82:83]
	v_pk_add_f32 v[38:39], v[38:39], v[94:95]
	v_pk_add_f32 v[36:37], v[36:37], v[92:93]
	v_pk_add_f32 v[34:35], v[34:35], v[90:91]
	global_store_dwordx4 v[48:49], v[40:43], off nt
	global_store_dwordx4 v[48:49], v[44:47], off offset:16 nt
	global_store_dwordx4 v[48:49], v[36:39], off offset:128 nt
	global_store_dwordx4 v[48:49], v[32:35], off offset:144 nt
	s_nop 1
	v_add_u32_e32 v32, 0xa0, v144
	v_ashrrev_i32_e32 v33, 31, v32
	v_lshlrev_b64 v[60:61], 12, v[32:33]
	v_lshl_add_u64 v[48:49], v[142:143], 0, v[60:61]
	global_load_dwordx4 v[40:43], v[48:49], off offset:16
	global_load_dwordx4 v[44:47], v[48:49], off
	global_load_dwordx4 v[32:35], v[48:49], off offset:144
	global_load_dwordx4 v[36:39], v[48:49], off offset:128
	v_add_u32_e32 v48, 0xb0, v144
	v_ashrrev_i32_e32 v49, 31, v48
	v_lshlrev_b64 v[62:63], 12, v[48:49]
	v_lshl_add_u64 v[68:69], v[142:143], 0, v[62:63]
	global_load_dwordx4 v[48:51], v[68:69], off offset:16
	global_load_dwordx4 v[56:59], v[68:69], off
	global_load_dwordx4 v[52:55], v[68:69], off offset:144
	global_load_dwordx4 v[64:67], v[68:69], off offset:128
	s_waitcnt vmcnt(0)
	v_pk_add_f32 v[26:27], v[26:27], v[42:43]
	v_pk_add_f32 v[30:31], v[30:31], v[46:47]
	v_pk_add_f32 v[12:13], v[12:13], v[32:33]
	v_lshl_add_u64 v[32:33], s[78:79], 0, v[60:61]
	v_pk_add_f32 v[28:29], v[28:29], v[44:45]
	v_lshl_add_u64 v[32:33], v[32:33], 0, v[140:141]
	v_pk_add_f32 v[24:25], v[24:25], v[40:41]
	v_pk_add_f32 v[22:23], v[22:23], v[38:39]
	v_pk_add_f32 v[20:21], v[20:21], v[36:37]
	v_pk_add_f32 v[14:15], v[14:15], v[34:35]
	global_store_dwordx4 v[32:33], v[28:31], off nt
	global_store_dwordx4 v[32:33], v[24:27], off offset:16 nt
	global_store_dwordx4 v[32:33], v[20:23], off offset:128 nt
	global_store_dwordx4 v[32:33], v[12:15], off offset:144 nt
	v_pk_add_f32 v[10:11], v[10:11], v[50:51]
	v_pk_add_f32 v[8:9], v[8:9], v[48:49]
	v_pk_add_f32 v[12:13], v[16:17], v[56:57]
	v_lshl_add_u64 v[16:17], s[78:79], 0, v[62:63]
	v_pk_add_f32 v[14:15], v[18:19], v[58:59]
	v_lshl_add_u64 v[16:17], v[16:17], 0, v[140:141]
	v_pk_add_f32 v[6:7], v[6:7], v[66:67]
	v_pk_add_f32 v[4:5], v[4:5], v[64:65]
	v_pk_add_f32 v[2:3], v[2:3], v[54:55]
	v_pk_add_f32 v[0:1], v[0:1], v[52:53]
	global_store_dwordx4 v[16:17], v[12:15], off nt
	global_store_dwordx4 v[16:17], v[8:11], off offset:16 nt
	global_store_dwordx4 v[16:17], v[4:7], off offset:128 nt
	global_store_dwordx4 v[16:17], v[0:3], off offset:144 nt
	s_cbranch_vccz .LBB0_877
	s_waitcnt vmcnt(0)
	s_cmpk_gt_u32 s16, 0xff
	s_cbranch_scc1 .LBB0_892
	s_barrier
